# write-through extended to the in-projection GEMM epilogue and the out-projection Y stores (every phase's last stores leave the L2 clean for the grid-barrier release)
# baseline (speedup 1.0000x reference)
.LBB0_285:
	s_add_i32 s0, s46, -16
	s_lshr_b32 s0, s0, 4
	s_add_i32 s0, s0, 1
	s_cmp_lt_i32 s46, 16
	v_readlane_b32 s1, v253, 43
	s_cselect_b32 s4, s68, s1
	v_readlane_b32 s1, v253, 44
	s_cselect_b32 s5, s69, s1
	s_cselect_b32 s6, 0, s0
	v_readlane_b32 s0, v255, 41
	v_readlane_b32 s1, v255, 42
	s_and_b64 s[0:1], s[0:1], exec
	s_cselect_b32 s1, s5, s99
	s_cselect_b32 s0, s4, s98
	v_readlane_b32 s4, v255, 6
	s_mul_i32 s4, s4, 9
	v_readlane_b32 s5, v255, 7
	s_add_i32 s4, s6, s4
	s_mul_hi_i32 s5, s4, 0x3000
	s_mulk_i32 s4, 0x3000
	v_readlane_b32 s6, v255, 8
	s_add_u32 s4, s6, s4
	v_readlane_b32 s6, v255, 9
	s_addc_u32 s5, s6, s5
	s_lshl_b32 s10, s56, 8
	s_ashr_i32 s11, s10, 31
	s_lshl_b64 s[18:19], s[10:11], 2
	s_add_u32 s4, s4, s18
	v_lshl_add_u32 v132, s46, 8, v250
	s_addc_u32 s5, s5, s19
	s_lshl_b32 s6, s2, 2
	v_ashrrev_i32_e32 v133, 31, v132
	s_add_u32 s18, s4, s6
	v_lshlrev_b64 v[132:133], 10, v[132:133]
	s_addc_u32 s19, s5, 0
	v_lshlrev_b32_e32 v208, 2, v220
	v_lshl_add_u64 v[144:145], v[132:133], 0, s[10:11]
	v_lshl_add_u64 v[128:129], s[18:19], 0, v[208:209]
	s_mov_b64 s[18:19], 0x2000
	s_movk_i32 s4, 0x2000
	v_or_b32_e32 v144, v144, v222
	v_lshl_add_u64 v[130:131], v[128:129], 0, s[18:19]
	v_add_co_u32_e32 v128, vcc, s4, v128
	v_lshlrev_b64 v[224:225], 2, v[144:145]
	s_nop 0
	v_addc_co_u32_e32 v129, vcc, 0, v129, vcc
	v_lshl_add_u64 v[226:227], s[0:1], 0, v[224:225]
	global_load_dwordx4 v[140:143], v[128:129], off
	global_load_dwordx4 v[136:139], v[130:131], off offset:64
	global_load_dwordx4 v[132:135], v[130:131], off offset:512
	s_nop 0
	global_load_dwordx4 v[128:131], v[130:131], off offset:576
	s_nop 0
	global_load_dwordx4 v[188:191], v[226:227], off nt
	global_load_dwordx4 v[192:195], v[226:227], off offset:64 nt
	global_load_dwordx4 v[200:203], v[226:227], off offset:512 nt
	global_load_dwordx4 v[204:207], v[226:227], off offset:576 nt
	s_mov_b32 s0, 0x10000
	v_add_co_u32_e32 v144, vcc, s0, v226
	s_mov_b32 s1, 0x20000
	s_nop 0
	v_addc_co_u32_e32 v145, vcc, 0, v227, vcc
	global_load_dwordx4 v[196:199], v[144:145], off nt
	global_load_dwordx4 v[184:187], v[144:145], off offset:64 nt
	global_load_dwordx4 v[180:183], v[144:145], off offset:512 nt
	global_load_dwordx4 v[176:179], v[144:145], off offset:576 nt
	v_add_co_u32_e32 v144, vcc, s1, v226
	s_mov_b32 s4, 0x30000
	s_nop 0
	v_addc_co_u32_e32 v145, vcc, 0, v227, vcc
	global_load_dwordx4 v[172:175], v[144:145], off nt
	global_load_dwordx4 v[168:171], v[144:145], off offset:64 nt
	global_load_dwordx4 v[164:167], v[144:145], off offset:512 nt
	global_load_dwordx4 v[160:163], v[144:145], off offset:576 nt
	v_add_co_u32_e32 v144, vcc, s4, v226
	v_lshl_add_u64 v[224:225], s[98:99], 0, v[224:225]
	s_nop 0
	v_addc_co_u32_e32 v145, vcc, 0, v227, vcc
	global_load_dwordx4 v[156:159], v[144:145], off nt
	global_load_dwordx4 v[152:155], v[144:145], off offset:64 nt
	global_load_dwordx4 v[148:151], v[144:145], off offset:512 nt
	s_nop 0
	global_load_dwordx4 v[144:147], v[144:145], off offset:576 nt
	s_mov_b32 s5, 0x80000
	s_waitcnt vmcnt(0)
	v_pk_mul_f32 v[190:191], v[190:191], s[28:29] op_sel_hi:[1,0]
	v_pk_mul_f32 v[188:189], v[188:189], s[28:29] op_sel_hi:[1,0]
	v_pk_fma_f32 v[190:191], v[126:127], v[142:143], v[190:191]
	v_pk_fma_f32 v[188:189], v[124:125], v[140:141], v[188:189]
	global_store_dwordx4 v[224:225], v[188:191], off sc1
	v_pk_mul_f32 v[192:193], v[192:193], s[28:29] op_sel_hi:[1,0]
	v_pk_mul_f32 v[198:199], v[198:199], s[28:29] op_sel_hi:[1,0]
	v_pk_mul_f32 v[188:189], v[194:195], s[28:29] op_sel_hi:[1,0]
	v_pk_mul_f32 v[196:197], v[196:197], s[28:29] op_sel_hi:[1,0]
	v_pk_fma_f32 v[190:191], v[122:123], v[138:139], v[188:189]
	v_pk_fma_f32 v[188:189], v[120:121], v[136:137], v[192:193]
	global_store_dwordx4 v[224:225], v[188:191], off offset:64 sc1
	v_pk_mul_f32 v[192:193], v[200:201], s[28:29] op_sel_hi:[1,0]
	v_pk_fma_f32 v[198:199], v[118:119], v[142:143], v[198:199]
	v_pk_mul_f32 v[188:189], v[202:203], s[28:29] op_sel_hi:[1,0]
	v_pk_fma_f32 v[196:197], v[116:117], v[140:141], v[196:197]
	v_pk_fma_f32 v[190:191], v[94:95], v[134:135], v[188:189]
	v_pk_fma_f32 v[188:189], v[92:93], v[132:133], v[192:193]
	global_store_dwordx4 v[224:225], v[188:191], off offset:512 sc1
	v_pk_mul_f32 v[192:193], v[204:205], s[28:29] op_sel_hi:[1,0]
	v_pk_mul_f32 v[186:187], v[186:187], s[28:29] op_sel_hi:[1,0]
	v_pk_mul_f32 v[188:189], v[206:207], s[28:29] op_sel_hi:[1,0]
	v_pk_mul_f32 v[184:185], v[184:185], s[28:29] op_sel_hi:[1,0]
	v_pk_fma_f32 v[190:191], v[90:91], v[130:131], v[188:189]
	v_pk_fma_f32 v[188:189], v[88:89], v[128:129], v[192:193]
	global_store_dwordx4 v[224:225], v[188:191], off offset:576 sc1
	v_pk_mul_f32 v[182:183], v[182:183], s[28:29] op_sel_hi:[1,0]
	v_pk_mul_f32 v[180:181], v[180:181], s[28:29] op_sel_hi:[1,0]
	v_add_co_u32_e32 v188, vcc, s5, v226
	v_pk_mul_f32 v[178:179], v[178:179], s[28:29] op_sel_hi:[1,0]
	s_nop 0
	v_addc_co_u32_e32 v189, vcc, 0, v227, vcc
	global_load_dwordx4 v[204:207], v[188:189], off nt
	global_load_dwordx4 v[200:203], v[188:189], off offset:64 nt
	global_load_dwordx4 v[192:195], v[188:189], off offset:512 nt
	s_nop 0
	global_load_dwordx4 v[188:191], v[188:189], off offset:576 nt
	v_add_co_u32_e32 v238, vcc, s0, v224
	v_pk_mul_f32 v[176:177], v[176:177], s[28:29] op_sel_hi:[1,0]
	s_nop 0
	v_addc_co_u32_e32 v239, vcc, 0, v225, vcc
	s_mov_b32 s0, 0x90000
	global_store_dwordx4 v[238:239], v[196:199], off sc1
	v_pk_fma_f32 v[186:187], v[114:115], v[138:139], v[186:187]
	v_pk_fma_f32 v[184:185], v[112:113], v[136:137], v[184:185]
	v_pk_fma_f32 v[182:183], v[86:87], v[134:135], v[182:183]
	v_pk_fma_f32 v[180:181], v[84:85], v[132:133], v[180:181]
	v_pk_fma_f32 v[178:179], v[82:83], v[130:131], v[178:179]
	v_pk_fma_f32 v[176:177], v[80:81], v[128:129], v[176:177]
	v_add_co_u32_e32 v196, vcc, s0, v226
	global_store_dwordx4 v[238:239], v[184:187], off offset:64 sc1
	global_store_dwordx4 v[238:239], v[180:183], off offset:512 sc1
	global_store_dwordx4 v[238:239], v[176:179], off offset:576 sc1
	v_addc_co_u32_e32 v197, vcc, 0, v227, vcc
	global_load_dwordx4 v[176:179], v[196:197], off nt
	global_load_dwordx4 v[180:183], v[196:197], off offset:64 nt
	global_load_dwordx4 v[184:187], v[196:197], off offset:512 nt
	s_nop 0
	global_load_dwordx4 v[196:199], v[196:197], off offset:576 nt
	v_pk_mul_f32 v[174:175], v[174:175], s[28:29] op_sel_hi:[1,0]
	v_pk_mul_f32 v[172:173], v[172:173], s[28:29] op_sel_hi:[1,0]
	v_add_co_u32_e32 v238, vcc, s1, v224
	v_pk_fma_f32 v[174:175], v[110:111], v[142:143], v[174:175]
	v_pk_fma_f32 v[172:173], v[108:109], v[140:141], v[172:173]
	v_addc_co_u32_e32 v239, vcc, 0, v225, vcc
	s_mov_b32 s1, 0xa0000
	global_store_dwordx4 v[238:239], v[172:175], off sc1
	v_pk_mul_f32 v[170:171], v[170:171], s[28:29] op_sel_hi:[1,0]
	v_pk_mul_f32 v[168:169], v[168:169], s[28:29] op_sel_hi:[1,0]
	v_pk_mul_f32 v[166:167], v[166:167], s[28:29] op_sel_hi:[1,0]
	v_pk_mul_f32 v[164:165], v[164:165], s[28:29] op_sel_hi:[1,0]
	v_pk_mul_f32 v[162:163], v[162:163], s[28:29] op_sel_hi:[1,0]
	v_pk_mul_f32 v[160:161], v[160:161], s[28:29] op_sel_hi:[1,0]
	v_add_co_u32_e32 v172, vcc, s1, v226
	v_pk_fma_f32 v[170:171], v[106:107], v[138:139], v[170:171]
	v_pk_fma_f32 v[168:169], v[104:105], v[136:137], v[168:169]
	v_pk_fma_f32 v[166:167], v[78:79], v[134:135], v[166:167]
	v_pk_fma_f32 v[164:165], v[76:77], v[132:133], v[164:165]
	v_pk_fma_f32 v[162:163], v[74:75], v[130:131], v[162:163]
	v_pk_fma_f32 v[160:161], v[72:73], v[128:129], v[160:161]
	v_addc_co_u32_e32 v173, vcc, 0, v227, vcc
	global_store_dwordx4 v[238:239], v[168:171], off offset:64 sc1
	global_store_dwordx4 v[238:239], v[164:167], off offset:512 sc1
	global_store_dwordx4 v[238:239], v[160:163], off offset:576 sc1
	v_pk_mul_f32 v[158:159], v[158:159], s[28:29] op_sel_hi:[1,0]
	v_pk_mul_f32 v[156:157], v[156:157], s[28:29] op_sel_hi:[1,0]
	v_add_co_u32_e32 v238, vcc, s4, v224
	v_pk_fma_f32 v[158:159], v[102:103], v[142:143], v[158:159]
	v_pk_fma_f32 v[156:157], v[100:101], v[140:141], v[156:157]
	v_addc_co_u32_e32 v239, vcc, 0, v225, vcc
	v_pk_mul_f32 v[154:155], v[154:155], s[28:29] op_sel_hi:[1,0]
	v_pk_mul_f32 v[152:153], v[152:153], s[28:29] op_sel_hi:[1,0]
	v_pk_mul_f32 v[150:151], v[150:151], s[28:29] op_sel_hi:[1,0]
	v_pk_mul_f32 v[148:149], v[148:149], s[28:29] op_sel_hi:[1,0]
	v_pk_mul_f32 v[146:147], v[146:147], s[28:29] op_sel_hi:[1,0]
	v_pk_mul_f32 v[144:145], v[144:145], s[28:29] op_sel_hi:[1,0]
	s_mov_b32 s4, 0xb0000
	global_load_dwordx4 v[160:163], v[172:173], off nt
	global_load_dwordx4 v[164:167], v[172:173], off offset:64 nt
	global_load_dwordx4 v[168:171], v[172:173], off offset:512 nt
	s_nop 0
	global_load_dwordx4 v[172:175], v[172:173], off offset:576 nt
	v_pk_fma_f32 v[154:155], v[98:99], v[138:139], v[154:155]
	global_store_dwordx4 v[238:239], v[156:159], off sc1
	v_pk_fma_f32 v[152:153], v[96:97], v[136:137], v[152:153]
	v_pk_fma_f32 v[150:151], v[70:71], v[134:135], v[150:151]
	v_pk_fma_f32 v[148:149], v[68:69], v[132:133], v[148:149]
	v_pk_fma_f32 v[146:147], v[66:67], v[130:131], v[146:147]
	v_pk_fma_f32 v[144:145], v[64:65], v[128:129], v[144:145]
	v_add_co_u32_e32 v156, vcc, s4, v226
	global_store_dwordx4 v[238:239], v[152:155], off offset:64 sc1
	global_store_dwordx4 v[238:239], v[148:151], off offset:512 sc1
	global_store_dwordx4 v[238:239], v[144:147], off offset:576 sc1
	v_addc_co_u32_e32 v157, vcc, 0, v227, vcc
	global_load_dwordx4 v[144:147], v[156:157], off nt
	global_load_dwordx4 v[148:151], v[156:157], off offset:64 nt
	global_load_dwordx4 v[152:155], v[156:157], off offset:512 nt
	s_nop 0
	global_load_dwordx4 v[156:159], v[156:157], off offset:576 nt
	v_add_co_u32_e32 v226, vcc, s5, v224
	s_waitcnt vmcnt(24)
	v_pk_mul_f32 v[190:191], v[190:191], s[28:29] op_sel_hi:[1,0]
	v_pk_mul_f32 v[188:189], v[188:189], s[28:29] op_sel_hi:[1,0]
	v_addc_co_u32_e32 v227, vcc, 0, v225, vcc
	v_pk_fma_f32 v[190:191], v[26:27], v[130:131], v[190:191]
	v_pk_fma_f32 v[188:189], v[24:25], v[128:129], v[188:189]
	global_store_dwordx4 v[226:227], v[188:191], off offset:576 sc1
	v_pk_mul_f32 v[204:205], v[204:205], s[28:29] op_sel_hi:[1,0]
	v_pk_mul_f32 v[206:207], v[206:207], s[28:29] op_sel_hi:[1,0]
	v_add_co_u32_e32 v188, vcc, s0, v224
	v_pk_fma_f32 v[204:205], v[60:61], v[140:141], v[204:205]
	s_nop 0
	v_addc_co_u32_e32 v189, vcc, 0, v225, vcc
	s_waitcnt vmcnt(20)
	v_pk_mul_f32 v[178:179], v[178:179], s[28:29] op_sel_hi:[1,0]
	v_pk_mul_f32 v[176:177], v[176:177], s[28:29] op_sel_hi:[1,0]
	v_pk_fma_f32 v[178:179], v[54:55], v[142:143], v[178:179]
	v_pk_fma_f32 v[176:177], v[52:53], v[140:141], v[176:177]
	global_store_dwordx4 v[188:189], v[176:179], off sc1
	s_waitcnt vmcnt(20)
	v_pk_mul_f32 v[180:181], v[180:181], s[28:29] op_sel_hi:[1,0]
	v_pk_fma_f32 v[206:207], v[62:63], v[142:143], v[206:207]
	v_pk_mul_f32 v[176:177], v[182:183], s[28:29] op_sel_hi:[1,0]
	v_pk_mul_f32 v[202:203], v[202:203], s[28:29] op_sel_hi:[1,0]
	v_pk_fma_f32 v[178:179], v[50:51], v[138:139], v[176:177]
	v_pk_fma_f32 v[176:177], v[48:49], v[136:137], v[180:181]
	global_store_dwordx4 v[188:189], v[176:179], off offset:64 sc1
	s_waitcnt vmcnt(20)
	v_pk_mul_f32 v[180:181], v[184:185], s[28:29] op_sel_hi:[1,0]
	v_pk_mul_f32 v[200:201], v[200:201], s[28:29] op_sel_hi:[1,0]
	v_pk_mul_f32 v[176:177], v[186:187], s[28:29] op_sel_hi:[1,0]
	v_pk_fma_f32 v[202:203], v[58:59], v[138:139], v[202:203]
	v_pk_fma_f32 v[178:179], v[22:23], v[134:135], v[176:177]
	v_pk_fma_f32 v[176:177], v[20:21], v[132:133], v[180:181]
	global_store_dwordx4 v[188:189], v[176:179], off offset:512 sc1
	s_waitcnt vmcnt(20)
	v_pk_mul_f32 v[180:181], v[196:197], s[28:29] op_sel_hi:[1,0]
	v_pk_fma_f32 v[200:201], v[56:57], v[136:137], v[200:201]
	v_pk_mul_f32 v[176:177], v[198:199], s[28:29] op_sel_hi:[1,0]
	v_pk_mul_f32 v[194:195], v[194:195], s[28:29] op_sel_hi:[1,0]
	v_pk_fma_f32 v[178:179], v[18:19], v[130:131], v[176:177]
	v_pk_fma_f32 v[176:177], v[16:17], v[128:129], v[180:181]
	global_store_dwordx4 v[188:189], v[176:179], off offset:576 sc1
	v_pk_mul_f32 v[192:193], v[192:193], s[28:29] op_sel_hi:[1,0]
	v_pk_fma_f32 v[194:195], v[30:31], v[134:135], v[194:195]
	v_add_co_u32_e32 v176, vcc, s1, v224
	v_pk_fma_f32 v[192:193], v[28:29], v[132:133], v[192:193]
	s_nop 0
	v_addc_co_u32_e32 v177, vcc, 0, v225, vcc
	global_store_dwordx4 v[226:227], v[204:207], off sc1
	global_store_dwordx4 v[226:227], v[200:203], off offset:64 sc1
	global_store_dwordx4 v[226:227], v[192:195], off offset:512 sc1
	s_waitcnt vmcnt(19)
	v_pk_mul_f32 v[160:161], v[160:161], s[28:29] op_sel_hi:[1,0]
	v_pk_mul_f32 v[162:163], v[162:163], s[28:29] op_sel_hi:[1,0]
	v_pk_fma_f32 v[160:161], v[44:45], v[140:141], v[160:161]
	v_pk_fma_f32 v[162:163], v[46:47], v[142:143], v[162:163]
	global_store_dwordx4 v[176:177], v[160:163], off sc1
	s_waitcnt vmcnt(19)
	v_pk_mul_f32 v[164:165], v[164:165], s[28:29] op_sel_hi:[1,0]
	s_waitcnt vmcnt(12)
	v_pk_mul_f32 v[144:145], v[144:145], s[28:29] op_sel_hi:[1,0]
	v_pk_mul_f32 v[146:147], v[146:147], s[28:29] op_sel_hi:[1,0]
	v_pk_fma_f32 v[140:141], v[36:37], v[140:141], v[144:145]
	v_add_co_u32_e32 v144, vcc, s4, v224
	v_pk_fma_f32 v[142:143], v[38:39], v[142:143], v[146:147]
	s_nop 0
	v_addc_co_u32_e32 v145, vcc, 0, v225, vcc
	v_pk_mul_f32 v[160:161], v[166:167], s[28:29] op_sel_hi:[1,0]
	global_store_dwordx4 v[144:145], v[140:143], off sc1
	v_pk_fma_f32 v[162:163], v[42:43], v[138:139], v[160:161]
	v_pk_fma_f32 v[160:161], v[40:41], v[136:137], v[164:165]
	s_waitcnt vmcnt(12)
	v_pk_mul_f32 v[140:141], v[150:151], s[28:29] op_sel_hi:[1,0]
	v_pk_mul_f32 v[142:143], v[148:149], s[28:29] op_sel_hi:[1,0]
	v_pk_fma_f32 v[138:139], v[34:35], v[138:139], v[140:141]
	v_pk_fma_f32 v[136:137], v[32:33], v[136:137], v[142:143]
	global_store_dwordx4 v[176:177], v[160:163], off offset:64 sc1
	v_pk_mul_f32 v[164:165], v[168:169], s[28:29] op_sel_hi:[1,0]
	global_store_dwordx4 v[144:145], v[136:139], off offset:64 sc1
	v_pk_mul_f32 v[160:161], v[170:171], s[28:29] op_sel_hi:[1,0]
	s_waitcnt vmcnt(13)
	v_pk_mul_f32 v[136:137], v[154:155], s[28:29] op_sel_hi:[1,0]
	v_pk_mul_f32 v[138:139], v[152:153], s[28:29] op_sel_hi:[1,0]
	v_pk_fma_f32 v[162:163], v[14:15], v[134:135], v[160:161]
	v_pk_fma_f32 v[160:161], v[12:13], v[132:133], v[164:165]
	v_pk_fma_f32 v[134:135], v[6:7], v[134:135], v[136:137]
	v_pk_fma_f32 v[132:133], v[4:5], v[132:133], v[138:139]
	global_store_dwordx4 v[176:177], v[160:163], off offset:512 sc1
	v_pk_mul_f32 v[164:165], v[172:173], s[28:29] op_sel_hi:[1,0]
	global_store_dwordx4 v[144:145], v[132:135], off offset:512 sc1
	v_pk_mul_f32 v[160:161], v[174:175], s[28:29] op_sel_hi:[1,0]
	s_waitcnt vmcnt(14)
	v_pk_mul_f32 v[132:133], v[158:159], s[28:29] op_sel_hi:[1,0]
	v_pk_mul_f32 v[134:135], v[156:157], s[28:29] op_sel_hi:[1,0]
	v_pk_fma_f32 v[162:163], v[10:11], v[130:131], v[160:161]
	v_pk_fma_f32 v[160:161], v[8:9], v[128:129], v[164:165]
	v_pk_fma_f32 v[130:131], v[2:3], v[130:131], v[132:133]
	v_pk_fma_f32 v[128:129], v[0:1], v[128:129], v[134:135]
	global_store_dwordx4 v[176:177], v[160:163], off offset:576 sc1
	global_store_dwordx4 v[144:145], v[128:131], off offset:576 sc1
	s_cbranch_execnz .LBB0_305

.LBB0_469:
	s_lshl_b32 s30, s17, 8
	s_add_i32 s30, s16, s30
	s_ashr_i32 s31, s30, 31
	s_lshl_b64 s[30:31], s[30:31], 1
	s_add_u32 s16, s46, s30
	s_addc_u32 s31, s47, s31
	s_lshl_b32 s30, s2, 1
	s_add_u32 s30, s16, s30
	s_addc_u32 s31, s31, 0
	v_lshlrev_b32_e32 v208, 1, v140
	v_lshl_add_u64 v[152:153], s[30:31], 0, v[208:209]
	v_ashrrev_i32_e32 v151, 31, v150
	v_lshl_add_u64 v[152:153], v[152:153], 0, v[142:143]
	v_lshlrev_b64 v[154:155], 11, v[150:151]
	v_cvt_pk_bf16_f32 v128, v128, v129
	v_cvt_pk_bf16_f32 v129, v130, v131
	v_cvt_pk_bf16_f32 v130, v132, v133
	v_cvt_pk_bf16_f32 v131, v134, v135
	v_lshl_add_u64 v[154:155], v[152:153], 0, v[154:155]
	v_permlane16_swap_b32_e32 v128, v130
	v_permlane16_swap_b32_e32 v129, v131
	global_store_dwordx4 v[154:155], v[128:131], off sc1
	v_mov_b64_e32 v[134:135], v[114:115]
	s_andn2_b64 vcc, exec, s[18:19]
	v_cndmask_b32_e64 v128, 0, 1, s[18:19]
	v_cmp_ne_u32_e64 s[46:47], 1, v128
	v_mov_b64_e32 v[130:131], v[118:119]
	v_mov_b64_e32 v[128:129], v[116:117]
	v_mov_b64_e32 v[132:133], v[112:113]
	s_cbranch_vccnz .LBB0_471
	v_mul_f32_e32 v128, 0xbfb8aa3b, v116
	v_mul_f32_e32 v129, 0xbfb8aa3b, v117
	v_mul_f32_e32 v130, 0xbfb8aa3b, v118
	v_mul_f32_e32 v131, 0xbfb8aa3b, v119
	v_mul_f32_e32 v132, 0xbfb8aa3b, v112
	v_mul_f32_e32 v133, 0xbfb8aa3b, v113
	v_mul_f32_e32 v134, 0xbfb8aa3b, v114
	v_mul_f32_e32 v135, 0xbfb8aa3b, v115
	v_exp_f32_e32 v128, v128
	v_exp_f32_e32 v129, v129
	v_exp_f32_e32 v130, v130
	v_exp_f32_e32 v131, v131
	v_exp_f32_e32 v132, v132
	v_exp_f32_e32 v133, v133
	v_exp_f32_e32 v134, v134
	v_exp_f32_e32 v135, v135
	v_add_f32_e32 v128, 1.0, v128
	v_add_f32_e32 v129, 1.0, v129
	v_add_f32_e32 v130, 1.0, v130
	v_add_f32_e32 v131, 1.0, v131
	v_add_f32_e32 v132, 1.0, v132
	v_add_f32_e32 v133, 1.0, v133
	v_add_f32_e32 v134, 1.0, v134
	v_add_f32_e32 v135, 1.0, v135
	v_rcp_f32_e32 v128, v128
	v_rcp_f32_e32 v129, v129
	v_rcp_f32_e32 v130, v130
	v_rcp_f32_e32 v131, v131
	v_rcp_f32_e32 v132, v132
	v_rcp_f32_e32 v134, v134
	v_rcp_f32_e32 v135, v135
	v_rcp_f32_e32 v133, v133
	v_pk_mul_f32 v[130:131], v[118:119], v[130:131]
	v_pk_mul_f32 v[128:129], v[116:117], v[128:129]
	v_pk_mul_f32 v[134:135], v[114:115], v[134:135]
	v_pk_mul_f32 v[132:133], v[112:113], v[132:133]
.LBB0_471:
	v_cvt_pk_bf16_f32 v128, v128, v129
	v_cvt_pk_bf16_f32 v129, v130, v131
	v_cvt_pk_bf16_f32 v130, v132, v133
	v_cvt_pk_bf16_f32 v131, v134, v135
	s_nop 0
	v_permlane16_swap_b32_e32 v128, v130
	v_permlane16_swap_b32_e32 v129, v131
	global_store_dwordx4 v[154:155], v[128:131], off offset:256 sc1
	v_mov_b64_e32 v[134:135], v[106:107]
	s_and_b64 vcc, exec, s[46:47]
	v_mov_b64_e32 v[130:131], v[110:111]
	v_mov_b64_e32 v[128:129], v[108:109]
	v_mov_b64_e32 v[132:133], v[104:105]
	s_cbranch_vccnz .LBB0_473
	v_mul_f32_e32 v128, 0xbfb8aa3b, v108
	v_mul_f32_e32 v129, 0xbfb8aa3b, v109
	v_mul_f32_e32 v130, 0xbfb8aa3b, v110
	v_mul_f32_e32 v131, 0xbfb8aa3b, v111
	v_mul_f32_e32 v132, 0xbfb8aa3b, v104
	v_mul_f32_e32 v133, 0xbfb8aa3b, v105
	v_mul_f32_e32 v134, 0xbfb8aa3b, v106
	v_mul_f32_e32 v135, 0xbfb8aa3b, v107
	v_exp_f32_e32 v128, v128
	v_exp_f32_e32 v129, v129
	v_exp_f32_e32 v130, v130
	v_exp_f32_e32 v131, v131
	v_exp_f32_e32 v132, v132
	v_exp_f32_e32 v133, v133
	v_exp_f32_e32 v134, v134
	v_exp_f32_e32 v135, v135
	v_add_f32_e32 v128, 1.0, v128
	v_add_f32_e32 v129, 1.0, v129
	v_add_f32_e32 v130, 1.0, v130
	v_add_f32_e32 v131, 1.0, v131
	v_add_f32_e32 v132, 1.0, v132
	v_add_f32_e32 v133, 1.0, v133
	v_add_f32_e32 v134, 1.0, v134
	v_add_f32_e32 v135, 1.0, v135
	v_rcp_f32_e32 v128, v128
	v_rcp_f32_e32 v129, v129
	v_rcp_f32_e32 v130, v130
	v_rcp_f32_e32 v131, v131
	v_rcp_f32_e32 v132, v132
	v_rcp_f32_e32 v134, v134
	v_rcp_f32_e32 v135, v135
	v_rcp_f32_e32 v133, v133
	v_pk_mul_f32 v[130:131], v[110:111], v[130:131]
	v_pk_mul_f32 v[128:129], v[108:109], v[128:129]
	v_pk_mul_f32 v[134:135], v[106:107], v[134:135]
	v_pk_mul_f32 v[132:133], v[104:105], v[132:133]
.LBB0_473:
	v_or_b32_e32 v154, 16, v150
	v_ashrrev_i32_e32 v155, 31, v154
	v_lshlrev_b64 v[154:155], 11, v[154:155]
	v_cvt_pk_bf16_f32 v128, v128, v129
	v_cvt_pk_bf16_f32 v129, v130, v131
	v_cvt_pk_bf16_f32 v130, v132, v133
	v_cvt_pk_bf16_f32 v131, v134, v135
	v_lshl_add_u64 v[154:155], v[152:153], 0, v[154:155]
	v_permlane16_swap_b32_e32 v128, v130
	v_permlane16_swap_b32_e32 v129, v131
	global_store_dwordx4 v[154:155], v[128:131], off sc1
	v_mov_b64_e32 v[134:135], v[98:99]
	s_and_b64 vcc, exec, s[46:47]
	v_mov_b64_e32 v[130:131], v[102:103]
	v_mov_b64_e32 v[128:129], v[100:101]
	v_mov_b64_e32 v[132:133], v[96:97]
	s_cbranch_vccnz .LBB0_475
	v_mul_f32_e32 v128, 0xbfb8aa3b, v100
	v_mul_f32_e32 v129, 0xbfb8aa3b, v101
	v_mul_f32_e32 v130, 0xbfb8aa3b, v102
	v_mul_f32_e32 v131, 0xbfb8aa3b, v103
	v_mul_f32_e32 v132, 0xbfb8aa3b, v96
	v_mul_f32_e32 v133, 0xbfb8aa3b, v97
	v_mul_f32_e32 v134, 0xbfb8aa3b, v98
	v_mul_f32_e32 v135, 0xbfb8aa3b, v99
	v_exp_f32_e32 v128, v128
	v_exp_f32_e32 v129, v129
	v_exp_f32_e32 v130, v130
	v_exp_f32_e32 v131, v131
	v_exp_f32_e32 v132, v132
	v_exp_f32_e32 v133, v133
	v_exp_f32_e32 v134, v134
	v_exp_f32_e32 v135, v135
	v_add_f32_e32 v128, 1.0, v128
	v_add_f32_e32 v129, 1.0, v129
	v_add_f32_e32 v130, 1.0, v130
	v_add_f32_e32 v131, 1.0, v131
	v_add_f32_e32 v132, 1.0, v132
	v_add_f32_e32 v133, 1.0, v133
	v_add_f32_e32 v134, 1.0, v134
	v_add_f32_e32 v135, 1.0, v135
	v_rcp_f32_e32 v128, v128
	v_rcp_f32_e32 v129, v129
	v_rcp_f32_e32 v130, v130
	v_rcp_f32_e32 v131, v131
	v_rcp_f32_e32 v132, v132
	v_rcp_f32_e32 v134, v134
	v_rcp_f32_e32 v135, v135
	v_rcp_f32_e32 v133, v133
	v_pk_mul_f32 v[130:131], v[102:103], v[130:131]
	v_pk_mul_f32 v[128:129], v[100:101], v[128:129]
	v_pk_mul_f32 v[134:135], v[98:99], v[134:135]
	v_pk_mul_f32 v[132:133], v[96:97], v[132:133]
.LBB0_475:
	v_cvt_pk_bf16_f32 v128, v128, v129
	v_cvt_pk_bf16_f32 v129, v130, v131
	v_cvt_pk_bf16_f32 v130, v132, v133
	v_cvt_pk_bf16_f32 v131, v134, v135
	s_nop 0
	v_permlane16_swap_b32_e32 v128, v130
	v_permlane16_swap_b32_e32 v129, v131
	global_store_dwordx4 v[154:155], v[128:131], off offset:256 sc1
	v_mov_b64_e32 v[134:135], v[90:91]
	s_and_b64 vcc, exec, s[46:47]
	v_mov_b64_e32 v[130:131], v[94:95]
	v_mov_b64_e32 v[128:129], v[92:93]
	v_mov_b64_e32 v[132:133], v[88:89]
	s_cbranch_vccnz .LBB0_477
	v_mul_f32_e32 v128, 0xbfb8aa3b, v92
	v_mul_f32_e32 v129, 0xbfb8aa3b, v93
	v_mul_f32_e32 v130, 0xbfb8aa3b, v94
	v_mul_f32_e32 v131, 0xbfb8aa3b, v95
	v_mul_f32_e32 v132, 0xbfb8aa3b, v88
	v_mul_f32_e32 v133, 0xbfb8aa3b, v89
	v_mul_f32_e32 v134, 0xbfb8aa3b, v90
	v_mul_f32_e32 v135, 0xbfb8aa3b, v91
	v_exp_f32_e32 v128, v128
	v_exp_f32_e32 v129, v129
	v_exp_f32_e32 v130, v130
	v_exp_f32_e32 v131, v131
	v_exp_f32_e32 v132, v132
	v_exp_f32_e32 v133, v133
	v_exp_f32_e32 v134, v134
	v_exp_f32_e32 v135, v135
	v_add_f32_e32 v128, 1.0, v128
	v_add_f32_e32 v129, 1.0, v129
	v_add_f32_e32 v130, 1.0, v130
	v_add_f32_e32 v131, 1.0, v131
	v_add_f32_e32 v132, 1.0, v132
	v_add_f32_e32 v133, 1.0, v133
	v_add_f32_e32 v134, 1.0, v134
	v_add_f32_e32 v135, 1.0, v135
	v_rcp_f32_e32 v128, v128
	v_rcp_f32_e32 v129, v129
	v_rcp_f32_e32 v130, v130
	v_rcp_f32_e32 v131, v131
	v_rcp_f32_e32 v132, v132
	v_rcp_f32_e32 v134, v134
	v_rcp_f32_e32 v135, v135
	v_rcp_f32_e32 v133, v133
	v_pk_mul_f32 v[130:131], v[94:95], v[130:131]
	v_pk_mul_f32 v[128:129], v[92:93], v[128:129]
	v_pk_mul_f32 v[134:135], v[90:91], v[134:135]
	v_pk_mul_f32 v[132:133], v[88:89], v[132:133]
.LBB0_477:
	v_or_b32_e32 v154, 32, v150
	v_ashrrev_i32_e32 v155, 31, v154
	v_lshlrev_b64 v[154:155], 11, v[154:155]
	v_cvt_pk_bf16_f32 v128, v128, v129
	v_cvt_pk_bf16_f32 v129, v130, v131
	v_cvt_pk_bf16_f32 v130, v132, v133
	v_cvt_pk_bf16_f32 v131, v134, v135
	v_lshl_add_u64 v[154:155], v[152:153], 0, v[154:155]
	v_permlane16_swap_b32_e32 v128, v130
	v_permlane16_swap_b32_e32 v129, v131
	global_store_dwordx4 v[154:155], v[128:131], off sc1
	v_mov_b64_e32 v[134:135], v[82:83]
	s_and_b64 vcc, exec, s[46:47]
	v_mov_b64_e32 v[130:131], v[86:87]
	v_mov_b64_e32 v[128:129], v[84:85]
	v_mov_b64_e32 v[132:133], v[80:81]
	s_cbranch_vccnz .LBB0_479
	v_mul_f32_e32 v128, 0xbfb8aa3b, v84
	v_mul_f32_e32 v129, 0xbfb8aa3b, v85
	v_mul_f32_e32 v130, 0xbfb8aa3b, v86
	v_mul_f32_e32 v131, 0xbfb8aa3b, v87
	v_mul_f32_e32 v132, 0xbfb8aa3b, v80
	v_mul_f32_e32 v133, 0xbfb8aa3b, v81
	v_mul_f32_e32 v134, 0xbfb8aa3b, v82
	v_mul_f32_e32 v135, 0xbfb8aa3b, v83
	v_exp_f32_e32 v128, v128
	v_exp_f32_e32 v129, v129
	v_exp_f32_e32 v130, v130
	v_exp_f32_e32 v131, v131
	v_exp_f32_e32 v132, v132
	v_exp_f32_e32 v133, v133
	v_exp_f32_e32 v134, v134
	v_exp_f32_e32 v135, v135
	v_add_f32_e32 v128, 1.0, v128
	v_add_f32_e32 v129, 1.0, v129
	v_add_f32_e32 v130, 1.0, v130
	v_add_f32_e32 v131, 1.0, v131
	v_add_f32_e32 v132, 1.0, v132
	v_add_f32_e32 v133, 1.0, v133
	v_add_f32_e32 v134, 1.0, v134
	v_add_f32_e32 v135, 1.0, v135
	v_rcp_f32_e32 v128, v128
	v_rcp_f32_e32 v129, v129
	v_rcp_f32_e32 v130, v130
	v_rcp_f32_e32 v131, v131
	v_rcp_f32_e32 v132, v132
	v_rcp_f32_e32 v134, v134
	v_rcp_f32_e32 v135, v135
	v_rcp_f32_e32 v133, v133
	v_pk_mul_f32 v[130:131], v[86:87], v[130:131]
	v_pk_mul_f32 v[128:129], v[84:85], v[128:129]
	v_pk_mul_f32 v[134:135], v[82:83], v[134:135]
	v_pk_mul_f32 v[132:133], v[80:81], v[132:133]
.LBB0_479:
	v_cvt_pk_bf16_f32 v128, v128, v129
	v_cvt_pk_bf16_f32 v129, v130, v131
	v_cvt_pk_bf16_f32 v130, v132, v133
	v_cvt_pk_bf16_f32 v131, v134, v135
	s_nop 0
	v_permlane16_swap_b32_e32 v128, v130
	v_permlane16_swap_b32_e32 v129, v131
	global_store_dwordx4 v[154:155], v[128:131], off offset:256 sc1
	v_mov_b64_e32 v[134:135], v[74:75]
	s_and_b64 vcc, exec, s[46:47]
	v_mov_b64_e32 v[130:131], v[78:79]
	v_mov_b64_e32 v[128:129], v[76:77]
	v_mov_b64_e32 v[132:133], v[72:73]
	s_cbranch_vccnz .LBB0_481
	v_mul_f32_e32 v128, 0xbfb8aa3b, v76
	v_mul_f32_e32 v129, 0xbfb8aa3b, v77
	v_mul_f32_e32 v130, 0xbfb8aa3b, v78
	v_mul_f32_e32 v131, 0xbfb8aa3b, v79
	v_mul_f32_e32 v132, 0xbfb8aa3b, v72
	v_mul_f32_e32 v133, 0xbfb8aa3b, v73
	v_mul_f32_e32 v134, 0xbfb8aa3b, v74
	v_mul_f32_e32 v135, 0xbfb8aa3b, v75
	v_exp_f32_e32 v128, v128
	v_exp_f32_e32 v129, v129
	v_exp_f32_e32 v130, v130
	v_exp_f32_e32 v131, v131
	v_exp_f32_e32 v132, v132
	v_exp_f32_e32 v133, v133
	v_exp_f32_e32 v134, v134
	v_exp_f32_e32 v135, v135
	v_add_f32_e32 v128, 1.0, v128
	v_add_f32_e32 v129, 1.0, v129
	v_add_f32_e32 v130, 1.0, v130
	v_add_f32_e32 v131, 1.0, v131
	v_add_f32_e32 v132, 1.0, v132
	v_add_f32_e32 v133, 1.0, v133
	v_add_f32_e32 v134, 1.0, v134
	v_add_f32_e32 v135, 1.0, v135
	v_rcp_f32_e32 v128, v128
	v_rcp_f32_e32 v129, v129
	v_rcp_f32_e32 v130, v130
	v_rcp_f32_e32 v131, v131
	v_rcp_f32_e32 v132, v132
	v_rcp_f32_e32 v134, v134
	v_rcp_f32_e32 v135, v135
	v_rcp_f32_e32 v133, v133
	v_pk_mul_f32 v[130:131], v[78:79], v[130:131]
	v_pk_mul_f32 v[128:129], v[76:77], v[128:129]
	v_pk_mul_f32 v[134:135], v[74:75], v[134:135]
	v_pk_mul_f32 v[132:133], v[72:73], v[132:133]
.LBB0_481:
	v_or_b32_e32 v154, 48, v150
	v_ashrrev_i32_e32 v155, 31, v154
	v_lshlrev_b64 v[154:155], 11, v[154:155]
	v_cvt_pk_bf16_f32 v128, v128, v129
	v_cvt_pk_bf16_f32 v129, v130, v131
	v_cvt_pk_bf16_f32 v130, v132, v133
	v_cvt_pk_bf16_f32 v131, v134, v135
	v_lshl_add_u64 v[154:155], v[152:153], 0, v[154:155]
	v_permlane16_swap_b32_e32 v128, v130
	v_permlane16_swap_b32_e32 v129, v131
	global_store_dwordx4 v[154:155], v[128:131], off sc1
	v_mov_b64_e32 v[134:135], v[66:67]
	s_and_b64 vcc, exec, s[46:47]
	v_mov_b64_e32 v[130:131], v[70:71]
	v_mov_b64_e32 v[128:129], v[68:69]
	v_mov_b64_e32 v[132:133], v[64:65]
	s_cbranch_vccnz .LBB0_483
	v_mul_f32_e32 v128, 0xbfb8aa3b, v68
	v_mul_f32_e32 v129, 0xbfb8aa3b, v69
	v_mul_f32_e32 v130, 0xbfb8aa3b, v70
	v_mul_f32_e32 v131, 0xbfb8aa3b, v71
	v_mul_f32_e32 v132, 0xbfb8aa3b, v64
	v_mul_f32_e32 v133, 0xbfb8aa3b, v65
	v_mul_f32_e32 v134, 0xbfb8aa3b, v66
	v_mul_f32_e32 v135, 0xbfb8aa3b, v67
	v_exp_f32_e32 v128, v128
	v_exp_f32_e32 v129, v129
	v_exp_f32_e32 v130, v130
	v_exp_f32_e32 v131, v131
	v_exp_f32_e32 v132, v132
	v_exp_f32_e32 v133, v133
	v_exp_f32_e32 v134, v134
	v_exp_f32_e32 v135, v135
	v_add_f32_e32 v128, 1.0, v128
	v_add_f32_e32 v129, 1.0, v129
	v_add_f32_e32 v130, 1.0, v130
	v_add_f32_e32 v131, 1.0, v131
	v_add_f32_e32 v132, 1.0, v132
	v_add_f32_e32 v133, 1.0, v133
	v_add_f32_e32 v134, 1.0, v134
	v_add_f32_e32 v135, 1.0, v135
	v_rcp_f32_e32 v128, v128
	v_rcp_f32_e32 v129, v129
	v_rcp_f32_e32 v130, v130
	v_rcp_f32_e32 v131, v131
	v_rcp_f32_e32 v132, v132
	v_rcp_f32_e32 v134, v134
	v_rcp_f32_e32 v135, v135
	v_rcp_f32_e32 v133, v133
	v_pk_mul_f32 v[130:131], v[70:71], v[130:131]
	v_pk_mul_f32 v[128:129], v[68:69], v[128:129]
	v_pk_mul_f32 v[134:135], v[66:67], v[134:135]
	v_pk_mul_f32 v[132:133], v[64:65], v[132:133]
.LBB0_483:
	v_cvt_pk_bf16_f32 v128, v128, v129
	v_cvt_pk_bf16_f32 v129, v130, v131
	v_cvt_pk_bf16_f32 v130, v132, v133
	v_cvt_pk_bf16_f32 v131, v134, v135
	s_nop 0
	v_permlane16_swap_b32_e32 v128, v130
	v_permlane16_swap_b32_e32 v129, v131
	global_store_dwordx4 v[154:155], v[128:131], off offset:256 sc1
	v_mov_b64_e32 v[134:135], v[58:59]
	s_and_b64 vcc, exec, s[46:47]
	v_mov_b64_e32 v[130:131], v[62:63]
	v_mov_b64_e32 v[128:129], v[60:61]
	v_mov_b64_e32 v[132:133], v[56:57]
	s_cbranch_vccnz .LBB0_485
	v_mul_f32_e32 v128, 0xbfb8aa3b, v60
	v_mul_f32_e32 v129, 0xbfb8aa3b, v61
	v_mul_f32_e32 v130, 0xbfb8aa3b, v62
	v_mul_f32_e32 v131, 0xbfb8aa3b, v63
	v_mul_f32_e32 v132, 0xbfb8aa3b, v56
	v_mul_f32_e32 v133, 0xbfb8aa3b, v57
	v_mul_f32_e32 v134, 0xbfb8aa3b, v58
	v_mul_f32_e32 v135, 0xbfb8aa3b, v59
	v_exp_f32_e32 v128, v128
	v_exp_f32_e32 v129, v129
	v_exp_f32_e32 v130, v130
	v_exp_f32_e32 v131, v131
	v_exp_f32_e32 v132, v132
	v_exp_f32_e32 v133, v133
	v_exp_f32_e32 v134, v134
	v_exp_f32_e32 v135, v135
	v_add_f32_e32 v128, 1.0, v128
	v_add_f32_e32 v129, 1.0, v129
	v_add_f32_e32 v130, 1.0, v130
	v_add_f32_e32 v131, 1.0, v131
	v_add_f32_e32 v132, 1.0, v132
	v_add_f32_e32 v133, 1.0, v133
	v_add_f32_e32 v134, 1.0, v134
	v_add_f32_e32 v135, 1.0, v135
	v_rcp_f32_e32 v128, v128
	v_rcp_f32_e32 v129, v129
	v_rcp_f32_e32 v130, v130
	v_rcp_f32_e32 v131, v131
	v_rcp_f32_e32 v132, v132
	v_rcp_f32_e32 v134, v134
	v_rcp_f32_e32 v135, v135
	v_rcp_f32_e32 v133, v133
	v_pk_mul_f32 v[130:131], v[62:63], v[130:131]
	v_pk_mul_f32 v[128:129], v[60:61], v[128:129]
	v_pk_mul_f32 v[134:135], v[58:59], v[134:135]
	v_pk_mul_f32 v[132:133], v[56:57], v[132:133]
.LBB0_485:
	v_lshlrev_b64 v[154:155], 11, v[150:151]
	v_lshl_add_u64 v[154:155], v[152:153], 0, v[154:155]
	v_cvt_pk_bf16_f32 v128, v128, v129
	v_cvt_pk_bf16_f32 v129, v130, v131
	v_cvt_pk_bf16_f32 v130, v132, v133
	v_cvt_pk_bf16_f32 v131, v134, v135
	v_add_co_u32_e32 v132, vcc, 0x40000, v154
	v_permlane16_swap_b32_e32 v128, v130
	v_permlane16_swap_b32_e32 v129, v131
	v_addc_co_u32_e32 v133, vcc, 0, v155, vcc
	global_store_dwordx4 v[132:133], v[128:131], off sc1
	v_mov_b64_e32 v[134:135], v[50:51]
	s_and_b64 vcc, exec, s[46:47]
	v_mov_b64_e32 v[130:131], v[54:55]
	v_mov_b64_e32 v[128:129], v[52:53]
	v_mov_b64_e32 v[132:133], v[48:49]
	s_cbranch_vccnz .LBB0_487
	v_mul_f32_e32 v128, 0xbfb8aa3b, v52
	v_mul_f32_e32 v129, 0xbfb8aa3b, v53
	v_mul_f32_e32 v130, 0xbfb8aa3b, v54
	v_mul_f32_e32 v131, 0xbfb8aa3b, v55
	v_mul_f32_e32 v132, 0xbfb8aa3b, v48
	v_mul_f32_e32 v133, 0xbfb8aa3b, v49
	v_mul_f32_e32 v134, 0xbfb8aa3b, v50
	v_mul_f32_e32 v135, 0xbfb8aa3b, v51
	v_exp_f32_e32 v128, v128
	v_exp_f32_e32 v129, v129
	v_exp_f32_e32 v130, v130
	v_exp_f32_e32 v131, v131
	v_exp_f32_e32 v132, v132
	v_exp_f32_e32 v133, v133
	v_exp_f32_e32 v134, v134
	v_exp_f32_e32 v135, v135
	v_add_f32_e32 v128, 1.0, v128
	v_add_f32_e32 v129, 1.0, v129
	v_add_f32_e32 v130, 1.0, v130
	v_add_f32_e32 v131, 1.0, v131
	v_add_f32_e32 v132, 1.0, v132
	v_add_f32_e32 v133, 1.0, v133
	v_add_f32_e32 v134, 1.0, v134
	v_add_f32_e32 v135, 1.0, v135
	v_rcp_f32_e32 v128, v128
	v_rcp_f32_e32 v129, v129
	v_rcp_f32_e32 v130, v130
	v_rcp_f32_e32 v131, v131
	v_rcp_f32_e32 v132, v132
	v_rcp_f32_e32 v134, v134
	v_rcp_f32_e32 v135, v135
	v_rcp_f32_e32 v133, v133
	v_pk_mul_f32 v[130:131], v[54:55], v[130:131]
	v_pk_mul_f32 v[128:129], v[52:53], v[128:129]
	v_pk_mul_f32 v[134:135], v[50:51], v[134:135]
	v_pk_mul_f32 v[132:133], v[48:49], v[132:133]
.LBB0_487:
	s_mov_b64 s[18:19], 0x40000
	v_cvt_pk_bf16_f32 v128, v128, v129
	v_cvt_pk_bf16_f32 v129, v130, v131
	v_cvt_pk_bf16_f32 v130, v132, v133
	v_cvt_pk_bf16_f32 v131, v134, v135
	v_lshl_add_u64 v[154:155], v[154:155], 0, s[18:19]
	v_permlane16_swap_b32_e32 v128, v130
	v_permlane16_swap_b32_e32 v129, v131
	global_store_dwordx4 v[154:155], v[128:131], off offset:256 sc1
	v_mov_b64_e32 v[134:135], v[42:43]
	s_and_b64 vcc, exec, s[46:47]
	v_mov_b64_e32 v[130:131], v[46:47]
	v_mov_b64_e32 v[128:129], v[44:45]
	v_mov_b64_e32 v[132:133], v[40:41]
	s_cbranch_vccnz .LBB0_489
	v_mul_f32_e32 v128, 0xbfb8aa3b, v44
	v_mul_f32_e32 v129, 0xbfb8aa3b, v45
	v_mul_f32_e32 v130, 0xbfb8aa3b, v46
	v_mul_f32_e32 v131, 0xbfb8aa3b, v47
	v_mul_f32_e32 v132, 0xbfb8aa3b, v40
	v_mul_f32_e32 v133, 0xbfb8aa3b, v41
	v_mul_f32_e32 v134, 0xbfb8aa3b, v42
	v_mul_f32_e32 v135, 0xbfb8aa3b, v43
	v_exp_f32_e32 v128, v128
	v_exp_f32_e32 v129, v129
	v_exp_f32_e32 v130, v130
	v_exp_f32_e32 v131, v131
	v_exp_f32_e32 v132, v132
	v_exp_f32_e32 v133, v133
	v_exp_f32_e32 v134, v134
	v_exp_f32_e32 v135, v135
	v_add_f32_e32 v128, 1.0, v128
	v_add_f32_e32 v129, 1.0, v129
	v_add_f32_e32 v130, 1.0, v130
	v_add_f32_e32 v131, 1.0, v131
	v_add_f32_e32 v132, 1.0, v132
	v_add_f32_e32 v133, 1.0, v133
	v_add_f32_e32 v134, 1.0, v134
	v_add_f32_e32 v135, 1.0, v135
	v_rcp_f32_e32 v128, v128
	v_rcp_f32_e32 v129, v129
	v_rcp_f32_e32 v130, v130
	v_rcp_f32_e32 v131, v131
	v_rcp_f32_e32 v132, v132
	v_rcp_f32_e32 v134, v134
	v_rcp_f32_e32 v135, v135
	v_rcp_f32_e32 v133, v133
	v_pk_mul_f32 v[130:131], v[46:47], v[130:131]
	v_pk_mul_f32 v[128:129], v[44:45], v[128:129]
	v_pk_mul_f32 v[134:135], v[42:43], v[134:135]
	v_pk_mul_f32 v[132:133], v[40:41], v[132:133]
.LBB0_489:
	v_lshlrev_b64 v[154:155], 11, v[150:151]
	v_lshl_add_u64 v[154:155], v[152:153], 0, v[154:155]
	v_cvt_pk_bf16_f32 v128, v128, v129
	v_cvt_pk_bf16_f32 v129, v130, v131
	v_cvt_pk_bf16_f32 v130, v132, v133
	v_cvt_pk_bf16_f32 v131, v134, v135
	v_add_co_u32_e32 v132, vcc, 0x48000, v154
	v_permlane16_swap_b32_e32 v128, v130
	v_permlane16_swap_b32_e32 v129, v131
	v_addc_co_u32_e32 v133, vcc, 0, v155, vcc
	global_store_dwordx4 v[132:133], v[128:131], off sc1
	v_mov_b64_e32 v[134:135], v[34:35]
	s_and_b64 vcc, exec, s[46:47]
	v_mov_b64_e32 v[130:131], v[38:39]
	v_mov_b64_e32 v[128:129], v[36:37]
	v_mov_b64_e32 v[132:133], v[32:33]
	s_cbranch_vccnz .LBB0_491
	v_mul_f32_e32 v128, 0xbfb8aa3b, v36
	v_mul_f32_e32 v129, 0xbfb8aa3b, v37
	v_mul_f32_e32 v130, 0xbfb8aa3b, v38
	v_mul_f32_e32 v131, 0xbfb8aa3b, v39
	v_mul_f32_e32 v132, 0xbfb8aa3b, v32
	v_mul_f32_e32 v133, 0xbfb8aa3b, v33
	v_mul_f32_e32 v134, 0xbfb8aa3b, v34
	v_mul_f32_e32 v135, 0xbfb8aa3b, v35
	v_exp_f32_e32 v128, v128
	v_exp_f32_e32 v129, v129
	v_exp_f32_e32 v130, v130
	v_exp_f32_e32 v131, v131
	v_exp_f32_e32 v132, v132
	v_exp_f32_e32 v133, v133
	v_exp_f32_e32 v134, v134
	v_exp_f32_e32 v135, v135
	v_add_f32_e32 v128, 1.0, v128
	v_add_f32_e32 v129, 1.0, v129
	v_add_f32_e32 v130, 1.0, v130
	v_add_f32_e32 v131, 1.0, v131
	v_add_f32_e32 v132, 1.0, v132
	v_add_f32_e32 v133, 1.0, v133
	v_add_f32_e32 v134, 1.0, v134
	v_add_f32_e32 v135, 1.0, v135
	v_rcp_f32_e32 v128, v128
	v_rcp_f32_e32 v129, v129
	v_rcp_f32_e32 v130, v130
	v_rcp_f32_e32 v131, v131
	v_rcp_f32_e32 v132, v132
	v_rcp_f32_e32 v134, v134
	v_rcp_f32_e32 v135, v135
	v_rcp_f32_e32 v133, v133
	v_pk_mul_f32 v[130:131], v[38:39], v[130:131]
	v_pk_mul_f32 v[128:129], v[36:37], v[128:129]
	v_pk_mul_f32 v[134:135], v[34:35], v[134:135]
	v_pk_mul_f32 v[132:133], v[32:33], v[132:133]
.LBB0_491:
	s_mov_b64 s[18:19], 0x48000
	v_cvt_pk_bf16_f32 v128, v128, v129
	v_cvt_pk_bf16_f32 v129, v130, v131
	v_cvt_pk_bf16_f32 v130, v132, v133
	v_cvt_pk_bf16_f32 v131, v134, v135
	v_lshl_add_u64 v[154:155], v[154:155], 0, s[18:19]
	v_permlane16_swap_b32_e32 v128, v130
	v_permlane16_swap_b32_e32 v129, v131
	global_store_dwordx4 v[154:155], v[128:131], off offset:256 sc1
	v_mov_b64_e32 v[134:135], v[26:27]
	s_and_b64 vcc, exec, s[46:47]
	v_mov_b64_e32 v[130:131], v[30:31]
	v_mov_b64_e32 v[128:129], v[28:29]
	v_mov_b64_e32 v[132:133], v[24:25]
	s_cbranch_vccnz .LBB0_493
	v_mul_f32_e32 v128, 0xbfb8aa3b, v28
	v_mul_f32_e32 v129, 0xbfb8aa3b, v29
	v_mul_f32_e32 v130, 0xbfb8aa3b, v30
	v_mul_f32_e32 v131, 0xbfb8aa3b, v31
	v_mul_f32_e32 v132, 0xbfb8aa3b, v24
	v_mul_f32_e32 v133, 0xbfb8aa3b, v25
	v_mul_f32_e32 v134, 0xbfb8aa3b, v26
	v_mul_f32_e32 v135, 0xbfb8aa3b, v27
	v_exp_f32_e32 v128, v128
	v_exp_f32_e32 v129, v129
	v_exp_f32_e32 v130, v130
	v_exp_f32_e32 v131, v131
	v_exp_f32_e32 v132, v132
	v_exp_f32_e32 v133, v133
	v_exp_f32_e32 v134, v134
	v_exp_f32_e32 v135, v135
	v_add_f32_e32 v128, 1.0, v128
	v_add_f32_e32 v129, 1.0, v129
	v_add_f32_e32 v130, 1.0, v130
	v_add_f32_e32 v131, 1.0, v131
	v_add_f32_e32 v132, 1.0, v132
	v_add_f32_e32 v133, 1.0, v133
	v_add_f32_e32 v134, 1.0, v134
	v_add_f32_e32 v135, 1.0, v135
	v_rcp_f32_e32 v128, v128
	v_rcp_f32_e32 v129, v129
	v_rcp_f32_e32 v130, v130
	v_rcp_f32_e32 v131, v131
	v_rcp_f32_e32 v132, v132
	v_rcp_f32_e32 v134, v134
	v_rcp_f32_e32 v135, v135
	v_rcp_f32_e32 v133, v133
	v_pk_mul_f32 v[130:131], v[30:31], v[130:131]
	v_pk_mul_f32 v[128:129], v[28:29], v[128:129]
	v_pk_mul_f32 v[134:135], v[26:27], v[134:135]
	v_pk_mul_f32 v[132:133], v[24:25], v[132:133]
.LBB0_493:
	v_lshlrev_b64 v[154:155], 11, v[150:151]
	v_lshl_add_u64 v[154:155], v[152:153], 0, v[154:155]
	v_cvt_pk_bf16_f32 v128, v128, v129
	v_cvt_pk_bf16_f32 v129, v130, v131
	v_cvt_pk_bf16_f32 v130, v132, v133
	v_cvt_pk_bf16_f32 v131, v134, v135
	v_add_co_u32_e32 v132, vcc, 0x50000, v154
	v_permlane16_swap_b32_e32 v128, v130
	v_permlane16_swap_b32_e32 v129, v131
	v_addc_co_u32_e32 v133, vcc, 0, v155, vcc
	global_store_dwordx4 v[132:133], v[128:131], off sc1
	v_mov_b64_e32 v[134:135], v[18:19]
	s_and_b64 vcc, exec, s[46:47]
	v_mov_b64_e32 v[130:131], v[22:23]
	v_mov_b64_e32 v[128:129], v[20:21]
	v_mov_b64_e32 v[132:133], v[16:17]
	s_cbranch_vccnz .LBB0_495
	v_mul_f32_e32 v128, 0xbfb8aa3b, v20
	v_mul_f32_e32 v129, 0xbfb8aa3b, v21
	v_mul_f32_e32 v130, 0xbfb8aa3b, v22
	v_mul_f32_e32 v131, 0xbfb8aa3b, v23
	v_mul_f32_e32 v132, 0xbfb8aa3b, v16
	v_mul_f32_e32 v133, 0xbfb8aa3b, v17
	v_mul_f32_e32 v134, 0xbfb8aa3b, v18
	v_mul_f32_e32 v135, 0xbfb8aa3b, v19
	v_exp_f32_e32 v128, v128
	v_exp_f32_e32 v129, v129
	v_exp_f32_e32 v130, v130
	v_exp_f32_e32 v131, v131
	v_exp_f32_e32 v132, v132
	v_exp_f32_e32 v133, v133
	v_exp_f32_e32 v134, v134
	v_exp_f32_e32 v135, v135
	v_add_f32_e32 v128, 1.0, v128
	v_add_f32_e32 v129, 1.0, v129
	v_add_f32_e32 v130, 1.0, v130
	v_add_f32_e32 v131, 1.0, v131
	v_add_f32_e32 v132, 1.0, v132
	v_add_f32_e32 v133, 1.0, v133
	v_add_f32_e32 v134, 1.0, v134
	v_add_f32_e32 v135, 1.0, v135
	v_rcp_f32_e32 v128, v128
	v_rcp_f32_e32 v129, v129
	v_rcp_f32_e32 v130, v130
	v_rcp_f32_e32 v131, v131
	v_rcp_f32_e32 v132, v132
	v_rcp_f32_e32 v134, v134
	v_rcp_f32_e32 v135, v135
	v_rcp_f32_e32 v133, v133
	v_pk_mul_f32 v[130:131], v[22:23], v[130:131]
	v_pk_mul_f32 v[128:129], v[20:21], v[128:129]
	v_pk_mul_f32 v[134:135], v[18:19], v[134:135]
	v_pk_mul_f32 v[132:133], v[16:17], v[132:133]
.LBB0_495:
	s_mov_b64 s[18:19], 0x50000
	v_cvt_pk_bf16_f32 v128, v128, v129
	v_cvt_pk_bf16_f32 v129, v130, v131
	v_cvt_pk_bf16_f32 v130, v132, v133
	v_cvt_pk_bf16_f32 v131, v134, v135
	v_lshl_add_u64 v[154:155], v[154:155], 0, s[18:19]
	v_permlane16_swap_b32_e32 v128, v130
	v_permlane16_swap_b32_e32 v129, v131
	global_store_dwordx4 v[154:155], v[128:131], off offset:256 sc1
	v_mov_b64_e32 v[134:135], v[10:11]
	s_and_b64 vcc, exec, s[46:47]
	v_mov_b64_e32 v[130:131], v[14:15]
	v_mov_b64_e32 v[128:129], v[12:13]
	v_mov_b64_e32 v[132:133], v[8:9]
	s_cbranch_vccnz .LBB0_497
	v_mul_f32_e32 v128, 0xbfb8aa3b, v12
	v_mul_f32_e32 v129, 0xbfb8aa3b, v13
	v_mul_f32_e32 v130, 0xbfb8aa3b, v14
	v_mul_f32_e32 v131, 0xbfb8aa3b, v15
	v_mul_f32_e32 v132, 0xbfb8aa3b, v8
	v_mul_f32_e32 v133, 0xbfb8aa3b, v9
	v_mul_f32_e32 v134, 0xbfb8aa3b, v10
	v_mul_f32_e32 v135, 0xbfb8aa3b, v11
	v_exp_f32_e32 v128, v128
	v_exp_f32_e32 v129, v129
	v_exp_f32_e32 v130, v130
	v_exp_f32_e32 v131, v131
	v_exp_f32_e32 v132, v132
	v_exp_f32_e32 v133, v133
	v_exp_f32_e32 v134, v134
	v_exp_f32_e32 v135, v135
	v_add_f32_e32 v128, 1.0, v128
	v_add_f32_e32 v129, 1.0, v129
	v_add_f32_e32 v130, 1.0, v130
	v_add_f32_e32 v131, 1.0, v131
	v_add_f32_e32 v132, 1.0, v132
	v_add_f32_e32 v133, 1.0, v133
	v_add_f32_e32 v134, 1.0, v134
	v_add_f32_e32 v135, 1.0, v135
	v_rcp_f32_e32 v128, v128
	v_rcp_f32_e32 v129, v129
	v_rcp_f32_e32 v130, v130
	v_rcp_f32_e32 v131, v131
	v_rcp_f32_e32 v132, v132
	v_rcp_f32_e32 v134, v134
	v_rcp_f32_e32 v135, v135
	v_rcp_f32_e32 v133, v133
	v_pk_mul_f32 v[130:131], v[14:15], v[130:131]
	v_pk_mul_f32 v[128:129], v[12:13], v[128:129]
	v_pk_mul_f32 v[134:135], v[10:11], v[134:135]
	v_pk_mul_f32 v[132:133], v[8:9], v[132:133]
.LBB0_497:
	v_lshlrev_b64 v[154:155], 11, v[150:151]
	v_lshl_add_u64 v[152:153], v[152:153], 0, v[154:155]
	v_cvt_pk_bf16_f32 v128, v128, v129
	v_cvt_pk_bf16_f32 v129, v130, v131
	v_cvt_pk_bf16_f32 v130, v132, v133
	v_cvt_pk_bf16_f32 v131, v134, v135
	v_add_co_u32_e32 v132, vcc, 0x58000, v152
	v_permlane16_swap_b32_e32 v128, v130
	v_permlane16_swap_b32_e32 v129, v131
	v_addc_co_u32_e32 v133, vcc, 0, v153, vcc
	global_store_dwordx4 v[132:133], v[128:131], off sc1
	v_mov_b64_e32 v[134:135], v[2:3]
	s_and_b64 vcc, exec, s[46:47]
	v_mov_b64_e32 v[130:131], v[6:7]
	v_mov_b64_e32 v[128:129], v[4:5]
	v_mov_b64_e32 v[132:133], v[0:1]
	s_cbranch_vccnz .LBB0_499
	v_mul_f32_e32 v128, 0xbfb8aa3b, v4
	v_mul_f32_e32 v129, 0xbfb8aa3b, v5
	v_mul_f32_e32 v130, 0xbfb8aa3b, v6
	v_mul_f32_e32 v131, 0xbfb8aa3b, v7
	v_mul_f32_e32 v132, 0xbfb8aa3b, v0
	v_mul_f32_e32 v133, 0xbfb8aa3b, v1
	v_mul_f32_e32 v134, 0xbfb8aa3b, v2
	v_mul_f32_e32 v135, 0xbfb8aa3b, v3
	v_exp_f32_e32 v128, v128
	v_exp_f32_e32 v129, v129
	v_exp_f32_e32 v130, v130
	v_exp_f32_e32 v131, v131
	v_exp_f32_e32 v132, v132
	v_exp_f32_e32 v133, v133
	v_exp_f32_e32 v134, v134
	v_exp_f32_e32 v135, v135
	v_add_f32_e32 v128, 1.0, v128
	v_add_f32_e32 v129, 1.0, v129
	v_add_f32_e32 v130, 1.0, v130
	v_add_f32_e32 v131, 1.0, v131
	v_add_f32_e32 v132, 1.0, v132
	v_add_f32_e32 v133, 1.0, v133
	v_add_f32_e32 v134, 1.0, v134
	v_add_f32_e32 v135, 1.0, v135
	v_rcp_f32_e32 v128, v128
	v_rcp_f32_e32 v129, v129
	v_rcp_f32_e32 v130, v130
	v_rcp_f32_e32 v131, v131
	v_rcp_f32_e32 v132, v132
	v_rcp_f32_e32 v134, v134
	v_rcp_f32_e32 v135, v135
	v_rcp_f32_e32 v133, v133
	v_pk_mul_f32 v[130:131], v[6:7], v[130:131]
	v_pk_mul_f32 v[128:129], v[4:5], v[128:129]
	v_pk_mul_f32 v[134:135], v[2:3], v[134:135]
	v_pk_mul_f32 v[132:133], v[0:1], v[132:133]
.LBB0_499:
	s_mov_b64 s[18:19], 0x58000
	v_cvt_pk_bf16_f32 v128, v128, v129
	v_cvt_pk_bf16_f32 v129, v130, v131
	v_cvt_pk_bf16_f32 v130, v132, v133
	v_cvt_pk_bf16_f32 v131, v134, v135
	v_lshl_add_u64 v[152:153], v[152:153], 0, s[18:19]
	v_permlane16_swap_b32_e32 v128, v130
	v_permlane16_swap_b32_e32 v129, v131
	global_store_dwordx4 v[152:153], v[128:131], off offset:256 sc1
	s_mov_b64 s[18:19], 0

.LBB0_509:
	s_lshl_b32 s16, s17, 7
	s_addk_i32 s16, 0x180
	s_and_b32 s16, s16, 0x180
	s_and_b64 s[18:19], s[18:19], exec
	v_mul_f32_e32 v132, v124, v132
	s_cselect_b32 s18, 0, 0x200
	v_cvt_pk_bf16_f32 v128, v132, v128
	s_or_b32 s16, s18, s16
	v_mul_f32_e32 v132, v120, v134
	v_ashrrev_i32_e32 v151, 31, v150
	v_cvt_pk_bf16_f32 v129, v129, v133
	v_or_b32_e32 v152, s16, v163
	v_cvt_pk_bf16_f32 v130, v132, v130
	v_lshlrev_b64 v[132:133], 11, v[150:151]
	v_lshl_add_u64 v[132:133], s[60:61], 0, v[132:133]
	v_lshlrev_b32_e32 v208, 1, v152
	v_cvt_pk_bf16_f32 v131, v131, v135
	v_lshl_add_u64 v[132:133], v[132:133], 0, v[208:209]
	v_permlane16_swap_b32_e32 v128, v130
	v_permlane16_swap_b32_e32 v129, v131
	v_lshl_add_u64 v[132:133], v[132:133], 0, v[142:143]
	s_and_b64 vcc, exec, s[46:47]
	s_mov_b64 s[18:19], -1
	global_store_dwordx4 v[132:133], v[128:131], off sc1
	s_cbranch_vccnz .LBB0_512
	s_nop 0
	v_mul_f32_e32 v128, v109, v101
	v_mul_f32_e32 v129, v110, v102
	v_mul_f32_e32 v133, v111, v103
	v_mov_b32_e32 v132, v100
	s_cbranch_execnz .LBB0_514
	s_branch .LBB0_513

.LBB0_518:
	v_mul_f32_e32 v132, v108, v132
	v_cvt_pk_bf16_f32 v128, v132, v128
	v_mul_f32_e32 v132, v104, v134
	v_cvt_pk_bf16_f32 v130, v132, v130
	v_or_b32_e32 v132, 16, v150
	v_cvt_pk_bf16_f32 v129, v129, v133
	v_ashrrev_i32_e32 v133, 31, v132
	v_lshlrev_b64 v[132:133], 11, v[132:133]
	v_lshl_add_u64 v[132:133], s[60:61], 0, v[132:133]
	v_cvt_pk_bf16_f32 v131, v131, v135
	v_lshl_add_u64 v[132:133], v[132:133], 0, v[208:209]
	v_permlane16_swap_b32_e32 v128, v130
	v_permlane16_swap_b32_e32 v129, v131
	v_lshl_add_u64 v[132:133], v[132:133], 0, v[142:143]
	s_and_b64 vcc, exec, s[46:47]
	s_mov_b64 s[18:19], -1
	global_store_dwordx4 v[132:133], v[128:131], off sc1
	s_cbranch_vccnz .LBB0_520
	s_nop 0
	v_mul_f32_e32 v128, v93, v85
	v_mul_f32_e32 v129, v94, v86
	v_mul_f32_e32 v133, v95, v87
	v_mov_b32_e32 v132, v84
	s_cbranch_execnz .LBB0_522
	s_branch .LBB0_521

.LBB0_526:
	v_mul_f32_e32 v132, v92, v132
	v_cvt_pk_bf16_f32 v128, v132, v128
	v_mul_f32_e32 v132, v88, v134
	v_cvt_pk_bf16_f32 v130, v132, v130
	v_or_b32_e32 v132, 32, v150
	v_cvt_pk_bf16_f32 v129, v129, v133
	v_ashrrev_i32_e32 v133, 31, v132
	v_lshlrev_b64 v[132:133], 11, v[132:133]
	v_lshl_add_u64 v[132:133], s[60:61], 0, v[132:133]
	v_cvt_pk_bf16_f32 v131, v131, v135
	v_lshl_add_u64 v[132:133], v[132:133], 0, v[208:209]
	v_permlane16_swap_b32_e32 v128, v130
	v_permlane16_swap_b32_e32 v129, v131
	v_lshl_add_u64 v[132:133], v[132:133], 0, v[142:143]
	s_and_b64 vcc, exec, s[46:47]
	s_mov_b64 s[18:19], -1
	global_store_dwordx4 v[132:133], v[128:131], off sc1
	s_cbranch_vccnz .LBB0_528
	s_nop 0
	v_mul_f32_e32 v128, v77, v69
	v_mul_f32_e32 v129, v78, v70
	v_mul_f32_e32 v133, v79, v71
	v_mov_b32_e32 v132, v68
	s_cbranch_execnz .LBB0_530
	s_branch .LBB0_529

.LBB0_534:
	v_mul_f32_e32 v132, v76, v132
	v_cvt_pk_bf16_f32 v128, v132, v128
	v_mul_f32_e32 v132, v72, v134
	v_cvt_pk_bf16_f32 v130, v132, v130
	v_or_b32_e32 v132, 48, v150
	v_cvt_pk_bf16_f32 v129, v129, v133
	v_ashrrev_i32_e32 v133, 31, v132
	v_lshlrev_b64 v[132:133], 11, v[132:133]
	v_lshl_add_u64 v[132:133], s[60:61], 0, v[132:133]
	v_cvt_pk_bf16_f32 v131, v131, v135
	v_lshl_add_u64 v[132:133], v[132:133], 0, v[208:209]
	v_permlane16_swap_b32_e32 v128, v130
	v_permlane16_swap_b32_e32 v129, v131
	v_lshl_add_u64 v[132:133], v[132:133], 0, v[142:143]
	s_and_b64 vcc, exec, s[46:47]
	s_mov_b64 s[18:19], -1
	global_store_dwordx4 v[132:133], v[128:131], off sc1
	s_cbranch_vccnz .LBB0_536
	s_nop 0
	v_mul_f32_e32 v128, v61, v53
	v_mul_f32_e32 v129, v62, v54
	v_mul_f32_e32 v133, v63, v55
	v_mov_b32_e32 v132, v52
	s_cbranch_execnz .LBB0_538
	s_branch .LBB0_537

.LBB0_542:
	v_mul_f32_e32 v132, v60, v132
	v_cvt_pk_bf16_f32 v128, v132, v128
	v_mul_f32_e32 v132, v56, v134
	v_cvt_pk_bf16_f32 v129, v129, v133
	v_cvt_pk_bf16_f32 v130, v132, v130
	v_lshlrev_b64 v[132:133], 11, v[150:151]
	v_lshl_add_u64 v[132:133], s[60:61], 0, v[132:133]
	v_lshl_add_u64 v[132:133], v[132:133], 0, v[208:209]
	v_lshl_add_u64 v[132:133], v[132:133], 0, v[142:143]
	v_add_co_u32_e32 v132, vcc, 0x40000, v132
	v_cvt_pk_bf16_f32 v131, v131, v135
	s_nop 0
	v_addc_co_u32_e32 v133, vcc, 0, v133, vcc
	v_permlane16_swap_b32_e32 v128, v130
	v_permlane16_swap_b32_e32 v129, v131
	s_and_b64 vcc, exec, s[46:47]
	s_mov_b64 s[18:19], -1
	global_store_dwordx4 v[132:133], v[128:131], off sc1
	s_cbranch_vccnz .LBB0_544
	s_nop 0
	v_mul_f32_e32 v128, v45, v37
	v_mul_f32_e32 v129, v46, v38
	v_mul_f32_e32 v133, v47, v39
	v_mov_b32_e32 v132, v36
	s_cbranch_execnz .LBB0_546
	s_branch .LBB0_545

.LBB0_550:
	v_mul_f32_e32 v132, v44, v132
	v_cvt_pk_bf16_f32 v128, v132, v128
	v_mul_f32_e32 v132, v40, v134
	v_cvt_pk_bf16_f32 v129, v129, v133
	v_cvt_pk_bf16_f32 v130, v132, v130
	v_lshlrev_b64 v[132:133], 11, v[150:151]
	v_lshl_add_u64 v[132:133], s[60:61], 0, v[132:133]
	v_lshl_add_u64 v[132:133], v[132:133], 0, v[208:209]
	v_lshl_add_u64 v[132:133], v[132:133], 0, v[142:143]
	v_add_co_u32_e32 v132, vcc, 0x48000, v132
	v_cvt_pk_bf16_f32 v131, v131, v135
	s_nop 0
	v_addc_co_u32_e32 v133, vcc, 0, v133, vcc
	v_permlane16_swap_b32_e32 v128, v130
	v_permlane16_swap_b32_e32 v129, v131
	s_and_b64 vcc, exec, s[46:47]
	s_mov_b64 s[18:19], -1
	global_store_dwordx4 v[132:133], v[128:131], off sc1
	s_cbranch_vccnz .LBB0_552
	s_nop 0
	v_mul_f32_e32 v128, v29, v21
	v_mul_f32_e32 v129, v30, v22
	v_mul_f32_e32 v133, v31, v23
	v_mov_b32_e32 v132, v20
	s_cbranch_execnz .LBB0_554
	s_branch .LBB0_553

.LBB0_558:
	v_mul_f32_e32 v132, v28, v132
	v_cvt_pk_bf16_f32 v128, v132, v128
	v_mul_f32_e32 v132, v24, v134
	v_cvt_pk_bf16_f32 v129, v129, v133
	v_cvt_pk_bf16_f32 v130, v132, v130
	v_lshlrev_b64 v[132:133], 11, v[150:151]
	v_lshl_add_u64 v[132:133], s[60:61], 0, v[132:133]
	v_lshl_add_u64 v[132:133], v[132:133], 0, v[208:209]
	v_lshl_add_u64 v[132:133], v[132:133], 0, v[142:143]
	v_add_co_u32_e32 v132, vcc, 0x50000, v132
	v_cvt_pk_bf16_f32 v131, v131, v135
	s_nop 0
	v_addc_co_u32_e32 v133, vcc, 0, v133, vcc
	v_permlane16_swap_b32_e32 v128, v130
	v_permlane16_swap_b32_e32 v129, v131
	s_and_b64 vcc, exec, s[46:47]
	s_mov_b64 s[18:19], -1
	global_store_dwordx4 v[132:133], v[128:131], off sc1
	s_cbranch_vccnz .LBB0_560
	s_nop 0
	v_mul_f32_e32 v128, v13, v5
	v_mul_f32_e32 v129, v14, v6
	v_mul_f32_e32 v133, v15, v7
	v_mov_b32_e32 v132, v4
	s_cbranch_execnz .LBB0_562
	s_branch .LBB0_561

.LBB0_566:
	v_mul_f32_e32 v132, v12, v132
	v_cvt_pk_bf16_f32 v128, v132, v128
	v_mul_f32_e32 v132, v8, v134
	v_cvt_pk_bf16_f32 v129, v129, v133
	v_cvt_pk_bf16_f32 v130, v132, v130
	v_lshlrev_b64 v[132:133], 11, v[150:151]
	v_lshl_add_u64 v[132:133], s[60:61], 0, v[132:133]
	v_lshl_add_u64 v[132:133], v[132:133], 0, v[208:209]
	v_lshl_add_u64 v[132:133], v[132:133], 0, v[142:143]
	v_cvt_pk_bf16_f32 v131, v131, v135
	v_add_co_u32_e32 v132, vcc, 0x58000, v132
	v_permlane16_swap_b32_e32 v128, v130
	v_permlane16_swap_b32_e32 v129, v131
	v_addc_co_u32_e32 v133, vcc, 0, v133, vcc
	global_store_dwordx4 v[132:133], v[128:131], off sc1
	s_mov_b64 s[18:19], 0

.LBB0_571:
	s_ashr_i32 s16, s1, 7
	s_and_b32 s16, s16, -2
	s_cmp_lg_u32 s36, 0
	s_cselect_b64 s[62:63], -1, 0
	v_cndmask_b32_e64 v156, 0, 1, s[30:31]
	s_and_b64 vcc, exec, s[62:63]
	v_ashrrev_i32_e32 v151, 31, v150
	v_pk_mul_f32 v[154:155], v[120:121], v[130:131]
	v_pk_mul_f32 v[152:153], v[120:121], v[128:129]
	v_cmp_ne_u32_e64 s[46:47], 1, v156
	s_cbranch_vccz .LBB0_651
	v_pk_mul_f32 v[166:167], v[122:123], v[132:133]
	v_pk_fma_f32 v[156:157], v[124:125], v[128:129], v[154:155] neg_lo:[0,0,1] neg_hi:[0,0,1]
	v_pk_fma_f32 v[170:171], v[126:127], v[134:135], v[166:167] neg_lo:[0,0,1] neg_hi:[0,0,1]
	v_pk_mul_f32 v[166:167], v[122:123], v[134:135]
	v_pk_fma_f32 v[168:169], v[124:125], v[130:131], v[152:153]
	v_pk_fma_f32 v[172:173], v[126:127], v[132:133], v[166:167]
	v_lshlrev_b64 v[174:175], 9, v[150:151]
	v_cvt_pk_bf16_f32 v166, v156, v157
	v_cvt_pk_bf16_f32 v167, v170, v171
	v_cvt_pk_bf16_f32 v168, v168, v169
	v_cvt_pk_bf16_f32 v169, v172, v173
	v_lshlrev_b32_e32 v165, 9, v150
	v_permlane16_swap_b32_e32 v166, v168
	v_permlane16_swap_b32_e32 v167, v169
	v_lshl_add_u64 v[156:157], v[144:145], 0, v[174:175]
	s_and_b64 vcc, exec, s[46:47]
	v_and_b32_e32 v208, 0x19e00, v165
	global_store_dwordx4 v[156:157], v[166:169], off sc1
	s_cbranch_vccnz .LBB0_574
	v_readlane_b32 s4, v255, 6
	s_add_i32 s30, s16, s4
	v_readlane_b32 s5, v255, 7
	s_ashr_i32 s31, s30, 31
	s_lshl_b64 s[30:31], s[30:31], 17
	v_readlane_b32 s4, v254, 1
	v_readlane_b32 s5, v254, 2
	s_add_u32 s30, s4, s30
	s_addc_u32 s31, s5, s31
	v_lshl_add_u64 v[166:167], s[30:31], 0, v[208:209]
	s_lshl_b32 s36, s2, 2
	v_lshl_add_u64 v[166:167], v[166:167], 0, s[36:37]
	v_lshlrev_b32_e32 v168, 2, v140
	v_mov_b32_e32 v169, v209
	v_lshl_add_u64 v[166:167], v[166:167], 0, v[168:169]
	global_store_dwordx4 v[166:167], v[124:127], off sc1
	global_store_dwordx4 v[166:167], v[120:123], off offset:64 sc1
.LBB0_574:
	s_nop 0
	v_cvt_pk_bf16_f32 v166, v116, v117
	v_cvt_pk_bf16_f32 v167, v118, v119
	v_cvt_pk_bf16_f32 v168, v112, v113
	v_cvt_pk_bf16_f32 v169, v114, v115
	s_nop 0
	v_permlane16_swap_b32_e32 v166, v168
	v_permlane16_swap_b32_e32 v167, v169
	s_and_b64 vcc, exec, s[46:47]
	global_store_dwordx4 v[156:157], v[166:169], off offset:256 sc1
	s_cbranch_vccnz .LBB0_576
	v_readlane_b32 s4, v255, 6
	s_add_i32 s30, s16, s4
	v_readlane_b32 s5, v255, 7
	s_ashr_i32 s31, s30, 31
	s_lshl_b64 s[30:31], s[30:31], 17
	v_readlane_b32 s4, v254, 3
	v_readlane_b32 s5, v254, 4
	s_add_u32 s30, s4, s30
	s_addc_u32 s31, s5, s31
	v_lshl_add_u64 v[120:121], s[30:31], 0, v[208:209]
	s_lshl_b32 s36, s2, 2
	v_lshl_add_u64 v[120:121], v[120:121], 0, s[36:37]
	v_lshlrev_b32_e32 v208, 2, v140
	v_lshl_add_u64 v[120:121], v[120:121], 0, v[208:209]
	global_store_dwordx4 v[120:121], v[116:119], off sc1
	global_store_dwordx4 v[120:121], v[112:115], off offset:64 sc1

.LBB0_577:
	v_lshlrev_b64 v[120:121], 10, v[150:151]
	s_lshl_b32 s30, s17, 8
	v_pk_fma_f32 v[154:155], v[124:125], v[128:129], v[154:155] neg_lo:[0,0,1] neg_hi:[0,0,1]
	v_pk_fma_f32 v[124:125], v[124:125], v[130:131], v[152:153]
	v_pk_mul_f32 v[152:153], v[122:123], v[132:133]
	v_pk_mul_f32 v[122:123], v[122:123], v[134:135]
	v_lshl_add_u64 v[120:121], s[56:57], 0, v[120:121]
	s_ashr_i32 s31, s30, 31
	v_pk_fma_f32 v[152:153], v[126:127], v[134:135], v[152:153] neg_lo:[0,0,1] neg_hi:[0,0,1]
	v_pk_fma_f32 v[122:123], v[126:127], v[132:133], v[122:123]
	v_lshl_add_u64 v[120:121], s[30:31], 1, v[120:121]
	s_lshl_b32 s36, s2, 1
	v_pk_mul_f32 v[154:155], v[154:155], s[22:23] op_sel_hi:[1,0]
	v_pk_mul_f32 v[124:125], v[124:125], s[22:23] op_sel_hi:[1,0]
	v_pk_mul_f32 v[152:153], v[152:153], s[22:23] op_sel_hi:[1,0]
	v_pk_mul_f32 v[126:127], v[122:123], s[22:23] op_sel_hi:[1,0]
	v_lshl_add_u64 v[120:121], v[120:121], 0, s[36:37]
	v_lshl_add_u64 v[156:157], v[120:121], 0, v[208:209]
	v_cvt_pk_bf16_f32 v120, v154, v155
	v_cvt_pk_bf16_f32 v121, v152, v153
	v_cvt_pk_bf16_f32 v122, v124, v125
	v_cvt_pk_bf16_f32 v123, v126, v127
	s_nop 0
	v_permlane16_swap_b32_e32 v120, v122
	v_permlane16_swap_b32_e32 v121, v123
	v_lshl_add_u64 v[124:125], v[156:157], 0, v[142:143]
	global_store_dwordx4 v[124:125], v[120:123], off sc1
	s_nop 1
	v_pk_mul_f32 v[120:121], v[112:113], v[130:131]
	v_pk_mul_f32 v[112:113], v[112:113], v[128:129]
	v_pk_fma_f32 v[120:121], v[116:117], v[128:129], v[120:121] neg_lo:[0,0,1] neg_hi:[0,0,1]
	v_pk_fma_f32 v[112:113], v[116:117], v[130:131], v[112:113]
	v_pk_mul_f32 v[120:121], v[120:121], s[22:23] op_sel_hi:[1,0]
	v_pk_mul_f32 v[116:117], v[112:113], s[22:23] op_sel_hi:[1,0]
	v_pk_mul_f32 v[112:113], v[114:115], v[132:133]
	s_nop 0
	v_pk_fma_f32 v[112:113], v[118:119], v[134:135], v[112:113] neg_lo:[0,0,1] neg_hi:[0,0,1]
	s_nop 0
	v_pk_mul_f32 v[122:123], v[112:113], s[22:23] op_sel_hi:[1,0]
	v_pk_mul_f32 v[112:113], v[114:115], v[134:135]
	v_cvt_pk_bf16_f32 v114, v116, v117
	v_pk_fma_f32 v[112:113], v[118:119], v[132:133], v[112:113]
	s_nop 0
	v_pk_mul_f32 v[118:119], v[112:113], s[22:23] op_sel_hi:[1,0]
	v_cvt_pk_bf16_f32 v112, v120, v121
	v_cvt_pk_bf16_f32 v113, v122, v123
	v_cvt_pk_bf16_f32 v115, v118, v119
	v_permlane16_swap_b32_e32 v112, v114
	s_nop 0
	v_permlane16_swap_b32_e32 v113, v115
	global_store_dwordx4 v[124:125], v[112:115], off offset:256 sc1

.LBB0_581:
	v_cndmask_b32_e64 v121, 0, 1, s[62:63]
	v_cmp_ne_u32_e64 s[50:51], 1, v121
	s_andn2_b64 vcc, exec, s[62:63]
	v_ashrrev_i32_e32 v121, 31, v120
	v_pk_mul_f32 v[124:125], v[104:105], v[114:115]
	v_pk_mul_f32 v[122:123], v[104:105], v[112:113]
	s_cbranch_vccnz .LBB0_652
	v_pk_mul_f32 v[130:131], v[106:107], v[116:117]
	v_pk_fma_f32 v[126:127], v[108:109], v[112:113], v[124:125] neg_lo:[0,0,1] neg_hi:[0,0,1]
	v_pk_fma_f32 v[132:133], v[110:111], v[118:119], v[130:131] neg_lo:[0,0,1] neg_hi:[0,0,1]
	v_pk_mul_f32 v[130:131], v[106:107], v[118:119]
	v_pk_fma_f32 v[128:129], v[108:109], v[114:115], v[122:123]
	v_pk_fma_f32 v[134:135], v[110:111], v[116:117], v[130:131]
	v_lshlrev_b64 v[152:153], 9, v[120:121]
	v_cvt_pk_bf16_f32 v130, v126, v127
	v_cvt_pk_bf16_f32 v131, v132, v133
	v_cvt_pk_bf16_f32 v132, v128, v129
	v_cvt_pk_bf16_f32 v133, v134, v135
	v_lshlrev_b32_e32 v126, 9, v120
	v_permlane16_swap_b32_e32 v130, v132
	v_permlane16_swap_b32_e32 v131, v133
	v_lshl_add_u64 v[128:129], v[144:145], 0, v[152:153]
	s_and_b64 vcc, exec, s[46:47]
	v_and_b32_e32 v126, 0x1be00, v126
	global_store_dwordx4 v[128:129], v[130:133], off sc1
	s_cbranch_vccnz .LBB0_584
	v_readlane_b32 s4, v255, 6
	s_add_i32 s18, s16, s4
	v_readlane_b32 s5, v255, 7
	s_ashr_i32 s19, s18, 31
	s_lshl_b64 s[18:19], s[18:19], 17
	v_readlane_b32 s4, v254, 1
	v_readlane_b32 s5, v254, 2
	s_add_u32 s18, s4, s18
	s_addc_u32 s19, s5, s19
	v_mov_b32_e32 v127, v209
	v_lshl_add_u64 v[130:131], s[18:19], 0, v[126:127]
	s_lshl_b32 s36, s2, 2
	v_lshl_add_u64 v[130:131], v[130:131], 0, s[36:37]
	v_lshlrev_b32_e32 v132, 2, v140
	v_mov_b32_e32 v133, v209
	v_lshl_add_u64 v[130:131], v[130:131], 0, v[132:133]
	global_store_dwordx4 v[130:131], v[108:111], off sc1
	global_store_dwordx4 v[130:131], v[104:107], off offset:64 sc1
.LBB0_584:
	s_nop 0
	v_cvt_pk_bf16_f32 v130, v100, v101
	v_cvt_pk_bf16_f32 v131, v102, v103
	v_cvt_pk_bf16_f32 v132, v96, v97
	v_cvt_pk_bf16_f32 v133, v98, v99
	s_nop 0
	v_permlane16_swap_b32_e32 v130, v132
	v_permlane16_swap_b32_e32 v131, v133
	s_and_b64 vcc, exec, s[46:47]
	global_store_dwordx4 v[128:129], v[130:133], off offset:256 sc1
	s_cbranch_vccnz .LBB0_586
	v_readlane_b32 s4, v255, 6
	s_add_i32 s18, s16, s4
	v_readlane_b32 s5, v255, 7
	s_ashr_i32 s19, s18, 31
	s_lshl_b64 s[18:19], s[18:19], 17
	v_readlane_b32 s4, v254, 3
	v_readlane_b32 s5, v254, 4
	s_add_u32 s18, s4, s18
	s_addc_u32 s19, s5, s19
	v_mov_b32_e32 v127, v209
	v_lshl_add_u64 v[104:105], s[18:19], 0, v[126:127]
	s_lshl_b32 s36, s2, 2
	v_lshl_add_u64 v[104:105], v[104:105], 0, s[36:37]
	v_lshlrev_b32_e32 v126, 2, v140
	v_lshl_add_u64 v[104:105], v[104:105], 0, v[126:127]
	global_store_dwordx4 v[104:105], v[100:103], off sc1
	global_store_dwordx4 v[104:105], v[96:99], off offset:64 sc1

.LBB0_587:
	v_lshlrev_b64 v[104:105], 10, v[120:121]
	s_lshl_b32 s18, s17, 8
	v_pk_fma_f32 v[120:121], v[108:109], v[112:113], v[124:125] neg_lo:[0,0,1] neg_hi:[0,0,1]
	v_pk_fma_f32 v[108:109], v[108:109], v[114:115], v[122:123]
	v_pk_mul_f32 v[122:123], v[106:107], v[116:117]
	v_pk_mul_f32 v[106:107], v[106:107], v[118:119]
	v_lshl_add_u64 v[104:105], s[56:57], 0, v[104:105]
	s_ashr_i32 s19, s18, 31
	v_pk_fma_f32 v[122:123], v[110:111], v[118:119], v[122:123] neg_lo:[0,0,1] neg_hi:[0,0,1]
	v_pk_fma_f32 v[106:107], v[110:111], v[116:117], v[106:107]
	v_lshl_add_u64 v[104:105], s[18:19], 1, v[104:105]
	s_lshl_b32 s36, s2, 1
	v_pk_mul_f32 v[120:121], v[120:121], s[22:23] op_sel_hi:[1,0]
	v_pk_mul_f32 v[108:109], v[108:109], s[22:23] op_sel_hi:[1,0]
	v_pk_mul_f32 v[122:123], v[122:123], s[22:23] op_sel_hi:[1,0]
	v_pk_mul_f32 v[110:111], v[106:107], s[22:23] op_sel_hi:[1,0]
	v_lshl_add_u64 v[104:105], v[104:105], 0, s[36:37]
	v_lshl_add_u64 v[124:125], v[104:105], 0, v[208:209]
	v_cvt_pk_bf16_f32 v104, v120, v121
	v_cvt_pk_bf16_f32 v105, v122, v123
	v_cvt_pk_bf16_f32 v106, v108, v109
	v_cvt_pk_bf16_f32 v107, v110, v111
	s_nop 0
	v_permlane16_swap_b32_e32 v104, v106
	v_permlane16_swap_b32_e32 v105, v107
	v_lshl_add_u64 v[108:109], v[124:125], 0, v[142:143]
	global_store_dwordx4 v[108:109], v[104:107], off sc1
	s_nop 1
	v_pk_mul_f32 v[104:105], v[96:97], v[114:115]
	v_pk_mul_f32 v[96:97], v[96:97], v[112:113]
	v_pk_fma_f32 v[104:105], v[100:101], v[112:113], v[104:105] neg_lo:[0,0,1] neg_hi:[0,0,1]
	v_pk_fma_f32 v[96:97], v[100:101], v[114:115], v[96:97]
	v_pk_mul_f32 v[104:105], v[104:105], s[22:23] op_sel_hi:[1,0]
	v_pk_mul_f32 v[100:101], v[96:97], s[22:23] op_sel_hi:[1,0]
	v_pk_mul_f32 v[96:97], v[98:99], v[116:117]
	s_nop 0
	v_pk_fma_f32 v[96:97], v[102:103], v[118:119], v[96:97] neg_lo:[0,0,1] neg_hi:[0,0,1]
	s_nop 0
	v_pk_mul_f32 v[106:107], v[96:97], s[22:23] op_sel_hi:[1,0]
	v_pk_mul_f32 v[96:97], v[98:99], v[118:119]
	v_cvt_pk_bf16_f32 v98, v100, v101
	v_pk_fma_f32 v[96:97], v[102:103], v[116:117], v[96:97]
	s_nop 0
	v_pk_mul_f32 v[102:103], v[96:97], s[22:23] op_sel_hi:[1,0]
	v_cvt_pk_bf16_f32 v96, v104, v105
	v_cvt_pk_bf16_f32 v97, v106, v107
	v_cvt_pk_bf16_f32 v99, v102, v103
	v_permlane16_swap_b32_e32 v96, v98
	s_nop 0
	v_permlane16_swap_b32_e32 v97, v99
	global_store_dwordx4 v[108:109], v[96:99], off offset:256 sc1

.LBB0_591:
	s_and_b64 vcc, exec, s[50:51]
	v_ashrrev_i32_e32 v105, 31, v104
	v_pk_mul_f32 v[108:109], v[88:89], v[98:99]
	v_pk_mul_f32 v[106:107], v[88:89], v[96:97]
	s_cbranch_vccnz .LBB0_653
	v_pk_mul_f32 v[114:115], v[90:91], v[100:101]
	v_pk_fma_f32 v[110:111], v[92:93], v[96:97], v[108:109] neg_lo:[0,0,1] neg_hi:[0,0,1]
	v_pk_fma_f32 v[116:117], v[94:95], v[102:103], v[114:115] neg_lo:[0,0,1] neg_hi:[0,0,1]
	v_pk_mul_f32 v[114:115], v[90:91], v[102:103]
	v_pk_fma_f32 v[112:113], v[92:93], v[98:99], v[106:107]
	v_pk_fma_f32 v[118:119], v[94:95], v[100:101], v[114:115]
	v_lshlrev_b64 v[120:121], 9, v[104:105]
	v_cvt_pk_bf16_f32 v114, v110, v111
	v_cvt_pk_bf16_f32 v115, v116, v117
	v_cvt_pk_bf16_f32 v116, v112, v113
	v_cvt_pk_bf16_f32 v117, v118, v119
	v_lshlrev_b32_e32 v110, 9, v104
	v_permlane16_swap_b32_e32 v114, v116
	v_permlane16_swap_b32_e32 v115, v117
	v_lshl_add_u64 v[112:113], v[144:145], 0, v[120:121]
	s_and_b64 vcc, exec, s[46:47]
	v_and_b32_e32 v110, 0x1de00, v110
	global_store_dwordx4 v[112:113], v[114:117], off sc1
	s_cbranch_vccnz .LBB0_594
	v_readlane_b32 s4, v255, 6
	s_add_i32 s18, s16, s4
	v_readlane_b32 s5, v255, 7
	s_ashr_i32 s19, s18, 31
	s_lshl_b64 s[18:19], s[18:19], 17
	v_readlane_b32 s4, v254, 1
	v_readlane_b32 s5, v254, 2
	s_add_u32 s18, s4, s18
	s_addc_u32 s19, s5, s19
	v_mov_b32_e32 v111, v209
	v_lshl_add_u64 v[114:115], s[18:19], 0, v[110:111]
	s_lshl_b32 s36, s2, 2
	v_lshl_add_u64 v[114:115], v[114:115], 0, s[36:37]
	v_lshlrev_b32_e32 v116, 2, v140
	v_mov_b32_e32 v117, v209
	v_lshl_add_u64 v[114:115], v[114:115], 0, v[116:117]
	global_store_dwordx4 v[114:115], v[92:95], off sc1
	global_store_dwordx4 v[114:115], v[88:91], off offset:64 sc1
.LBB0_594:
	s_nop 0
	v_cvt_pk_bf16_f32 v114, v84, v85
	v_cvt_pk_bf16_f32 v115, v86, v87
	v_cvt_pk_bf16_f32 v116, v80, v81
	v_cvt_pk_bf16_f32 v117, v82, v83
	s_nop 0
	v_permlane16_swap_b32_e32 v114, v116
	v_permlane16_swap_b32_e32 v115, v117
	s_and_b64 vcc, exec, s[46:47]
	global_store_dwordx4 v[112:113], v[114:117], off offset:256 sc1
	s_cbranch_vccnz .LBB0_596
	v_readlane_b32 s4, v255, 6
	s_add_i32 s18, s16, s4
	v_readlane_b32 s5, v255, 7
	s_ashr_i32 s19, s18, 31
	s_lshl_b64 s[18:19], s[18:19], 17
	v_readlane_b32 s4, v254, 3
	v_readlane_b32 s5, v254, 4
	s_add_u32 s18, s4, s18
	s_addc_u32 s19, s5, s19
	v_mov_b32_e32 v111, v209
	v_lshl_add_u64 v[88:89], s[18:19], 0, v[110:111]
	s_lshl_b32 s36, s2, 2
	v_lshl_add_u64 v[88:89], v[88:89], 0, s[36:37]
	v_lshlrev_b32_e32 v110, 2, v140
	v_lshl_add_u64 v[88:89], v[88:89], 0, v[110:111]
	global_store_dwordx4 v[88:89], v[84:87], off sc1
	global_store_dwordx4 v[88:89], v[80:83], off offset:64 sc1

.LBB0_597:
	v_lshlrev_b64 v[88:89], 10, v[104:105]
	s_lshl_b32 s18, s17, 8
	v_pk_fma_f32 v[104:105], v[92:93], v[96:97], v[108:109] neg_lo:[0,0,1] neg_hi:[0,0,1]
	v_pk_fma_f32 v[92:93], v[92:93], v[98:99], v[106:107]
	v_pk_mul_f32 v[106:107], v[90:91], v[100:101]
	v_pk_mul_f32 v[90:91], v[90:91], v[102:103]
	v_lshl_add_u64 v[88:89], s[56:57], 0, v[88:89]
	s_ashr_i32 s19, s18, 31
	v_pk_fma_f32 v[106:107], v[94:95], v[102:103], v[106:107] neg_lo:[0,0,1] neg_hi:[0,0,1]
	v_pk_fma_f32 v[90:91], v[94:95], v[100:101], v[90:91]
	v_lshl_add_u64 v[88:89], s[18:19], 1, v[88:89]
	s_lshl_b32 s36, s2, 1
	v_pk_mul_f32 v[104:105], v[104:105], s[22:23] op_sel_hi:[1,0]
	v_pk_mul_f32 v[92:93], v[92:93], s[22:23] op_sel_hi:[1,0]
	v_pk_mul_f32 v[106:107], v[106:107], s[22:23] op_sel_hi:[1,0]
	v_pk_mul_f32 v[94:95], v[90:91], s[22:23] op_sel_hi:[1,0]
	v_lshl_add_u64 v[88:89], v[88:89], 0, s[36:37]
	v_lshl_add_u64 v[108:109], v[88:89], 0, v[208:209]
	v_cvt_pk_bf16_f32 v88, v104, v105
	v_cvt_pk_bf16_f32 v89, v106, v107
	v_cvt_pk_bf16_f32 v90, v92, v93
	v_cvt_pk_bf16_f32 v91, v94, v95
	s_nop 0
	v_permlane16_swap_b32_e32 v88, v90
	v_permlane16_swap_b32_e32 v89, v91
	v_lshl_add_u64 v[92:93], v[108:109], 0, v[142:143]
	global_store_dwordx4 v[92:93], v[88:91], off sc1
	s_nop 1
	v_pk_mul_f32 v[88:89], v[80:81], v[98:99]
	v_pk_mul_f32 v[80:81], v[80:81], v[96:97]
	v_pk_fma_f32 v[88:89], v[84:85], v[96:97], v[88:89] neg_lo:[0,0,1] neg_hi:[0,0,1]
	v_pk_fma_f32 v[80:81], v[84:85], v[98:99], v[80:81]
	v_pk_mul_f32 v[88:89], v[88:89], s[22:23] op_sel_hi:[1,0]
	v_pk_mul_f32 v[84:85], v[80:81], s[22:23] op_sel_hi:[1,0]
	v_pk_mul_f32 v[80:81], v[82:83], v[100:101]
	s_nop 0
	v_pk_fma_f32 v[80:81], v[86:87], v[102:103], v[80:81] neg_lo:[0,0,1] neg_hi:[0,0,1]
	s_nop 0
	v_pk_mul_f32 v[90:91], v[80:81], s[22:23] op_sel_hi:[1,0]
	v_pk_mul_f32 v[80:81], v[82:83], v[102:103]
	v_cvt_pk_bf16_f32 v82, v84, v85
	v_pk_fma_f32 v[80:81], v[86:87], v[100:101], v[80:81]
	s_nop 0
	v_pk_mul_f32 v[86:87], v[80:81], s[22:23] op_sel_hi:[1,0]
	v_cvt_pk_bf16_f32 v80, v88, v89
	v_cvt_pk_bf16_f32 v81, v90, v91
	v_cvt_pk_bf16_f32 v83, v86, v87
	v_permlane16_swap_b32_e32 v80, v82
	s_nop 0
	v_permlane16_swap_b32_e32 v81, v83
	global_store_dwordx4 v[92:93], v[80:83], off offset:256 sc1

.LBB0_601:
	s_and_b64 vcc, exec, s[50:51]
	v_ashrrev_i32_e32 v89, 31, v88
	v_pk_mul_f32 v[92:93], v[72:73], v[82:83]
	v_pk_mul_f32 v[90:91], v[72:73], v[80:81]
	s_cbranch_vccnz .LBB0_654
	v_pk_mul_f32 v[98:99], v[74:75], v[84:85]
	v_pk_fma_f32 v[94:95], v[76:77], v[80:81], v[92:93] neg_lo:[0,0,1] neg_hi:[0,0,1]
	v_pk_fma_f32 v[100:101], v[78:79], v[86:87], v[98:99] neg_lo:[0,0,1] neg_hi:[0,0,1]
	v_pk_mul_f32 v[98:99], v[74:75], v[86:87]
	v_pk_fma_f32 v[96:97], v[76:77], v[82:83], v[90:91]
	v_pk_fma_f32 v[102:103], v[78:79], v[84:85], v[98:99]
	v_lshlrev_b64 v[104:105], 9, v[88:89]
	v_cvt_pk_bf16_f32 v98, v94, v95
	v_cvt_pk_bf16_f32 v99, v100, v101
	v_cvt_pk_bf16_f32 v100, v96, v97
	v_cvt_pk_bf16_f32 v101, v102, v103
	v_lshlrev_b32_e32 v94, 9, v88
	v_permlane16_swap_b32_e32 v98, v100
	v_permlane16_swap_b32_e32 v99, v101
	v_lshl_add_u64 v[96:97], v[144:145], 0, v[104:105]
	s_and_b64 vcc, exec, s[46:47]
	v_and_b32_e32 v94, 0x1fe00, v94
	global_store_dwordx4 v[96:97], v[98:101], off sc1
	s_cbranch_vccnz .LBB0_604
	v_readlane_b32 s4, v255, 6
	s_add_i32 s18, s16, s4
	v_readlane_b32 s5, v255, 7
	s_ashr_i32 s19, s18, 31
	s_lshl_b64 s[18:19], s[18:19], 17
	v_readlane_b32 s4, v254, 1
	v_readlane_b32 s5, v254, 2
	s_add_u32 s18, s4, s18
	s_addc_u32 s19, s5, s19
	v_mov_b32_e32 v95, v209
	v_lshl_add_u64 v[98:99], s[18:19], 0, v[94:95]
	s_lshl_b32 s36, s2, 2
	v_lshl_add_u64 v[98:99], v[98:99], 0, s[36:37]
	v_lshlrev_b32_e32 v100, 2, v140
	v_mov_b32_e32 v101, v209
	v_lshl_add_u64 v[98:99], v[98:99], 0, v[100:101]
	global_store_dwordx4 v[98:99], v[76:79], off sc1
	global_store_dwordx4 v[98:99], v[72:75], off offset:64 sc1
.LBB0_604:
	s_nop 0
	v_cvt_pk_bf16_f32 v98, v68, v69
	v_cvt_pk_bf16_f32 v99, v70, v71
	v_cvt_pk_bf16_f32 v100, v64, v65
	v_cvt_pk_bf16_f32 v101, v66, v67
	s_nop 0
	v_permlane16_swap_b32_e32 v98, v100
	v_permlane16_swap_b32_e32 v99, v101
	s_and_b64 vcc, exec, s[46:47]
	global_store_dwordx4 v[96:97], v[98:101], off offset:256 sc1
	s_cbranch_vccnz .LBB0_606
	v_readlane_b32 s4, v255, 6
	s_add_i32 s18, s16, s4
	v_readlane_b32 s5, v255, 7
	s_ashr_i32 s19, s18, 31
	s_lshl_b64 s[18:19], s[18:19], 17
	v_readlane_b32 s4, v254, 3
	v_readlane_b32 s5, v254, 4
	s_add_u32 s18, s4, s18
	s_addc_u32 s19, s5, s19
	v_mov_b32_e32 v95, v209
	v_lshl_add_u64 v[72:73], s[18:19], 0, v[94:95]
	s_lshl_b32 s36, s2, 2
	v_lshl_add_u64 v[72:73], v[72:73], 0, s[36:37]
	v_lshlrev_b32_e32 v94, 2, v140
	v_lshl_add_u64 v[72:73], v[72:73], 0, v[94:95]
	global_store_dwordx4 v[72:73], v[68:71], off sc1
	global_store_dwordx4 v[72:73], v[64:67], off offset:64 sc1

.LBB0_607:
	v_lshlrev_b64 v[72:73], 10, v[88:89]
	s_lshl_b32 s18, s17, 8
	v_pk_fma_f32 v[88:89], v[76:77], v[80:81], v[92:93] neg_lo:[0,0,1] neg_hi:[0,0,1]
	v_pk_fma_f32 v[76:77], v[76:77], v[82:83], v[90:91]
	v_pk_mul_f32 v[90:91], v[74:75], v[84:85]
	v_pk_mul_f32 v[74:75], v[74:75], v[86:87]
	v_lshl_add_u64 v[72:73], s[56:57], 0, v[72:73]
	s_ashr_i32 s19, s18, 31
	v_pk_fma_f32 v[90:91], v[78:79], v[86:87], v[90:91] neg_lo:[0,0,1] neg_hi:[0,0,1]
	v_pk_fma_f32 v[74:75], v[78:79], v[84:85], v[74:75]
	v_lshl_add_u64 v[72:73], s[18:19], 1, v[72:73]
	s_lshl_b32 s36, s2, 1
	v_pk_mul_f32 v[88:89], v[88:89], s[22:23] op_sel_hi:[1,0]
	v_pk_mul_f32 v[76:77], v[76:77], s[22:23] op_sel_hi:[1,0]
	v_pk_mul_f32 v[90:91], v[90:91], s[22:23] op_sel_hi:[1,0]
	v_pk_mul_f32 v[78:79], v[74:75], s[22:23] op_sel_hi:[1,0]
	v_lshl_add_u64 v[72:73], v[72:73], 0, s[36:37]
	v_lshl_add_u64 v[92:93], v[72:73], 0, v[208:209]
	v_cvt_pk_bf16_f32 v72, v88, v89
	v_cvt_pk_bf16_f32 v73, v90, v91
	v_cvt_pk_bf16_f32 v74, v76, v77
	v_cvt_pk_bf16_f32 v75, v78, v79
	s_nop 0
	v_permlane16_swap_b32_e32 v72, v74
	v_permlane16_swap_b32_e32 v73, v75
	v_lshl_add_u64 v[76:77], v[92:93], 0, v[142:143]
	global_store_dwordx4 v[76:77], v[72:75], off sc1
	s_nop 1
	v_pk_mul_f32 v[72:73], v[64:65], v[82:83]
	v_pk_mul_f32 v[64:65], v[64:65], v[80:81]
	v_pk_fma_f32 v[72:73], v[68:69], v[80:81], v[72:73] neg_lo:[0,0,1] neg_hi:[0,0,1]
	v_pk_fma_f32 v[64:65], v[68:69], v[82:83], v[64:65]
	v_pk_mul_f32 v[72:73], v[72:73], s[22:23] op_sel_hi:[1,0]
	v_pk_mul_f32 v[68:69], v[64:65], s[22:23] op_sel_hi:[1,0]
	v_pk_mul_f32 v[64:65], v[66:67], v[84:85]
	s_nop 0
	v_pk_fma_f32 v[64:65], v[70:71], v[86:87], v[64:65] neg_lo:[0,0,1] neg_hi:[0,0,1]
	s_nop 0
	v_pk_mul_f32 v[74:75], v[64:65], s[22:23] op_sel_hi:[1,0]
	v_pk_mul_f32 v[64:65], v[66:67], v[86:87]
	v_cvt_pk_bf16_f32 v66, v68, v69
	v_pk_fma_f32 v[64:65], v[70:71], v[84:85], v[64:65]
	s_nop 0
	v_pk_mul_f32 v[70:71], v[64:65], s[22:23] op_sel_hi:[1,0]
	v_cvt_pk_bf16_f32 v64, v72, v73
	v_cvt_pk_bf16_f32 v65, v74, v75
	v_cvt_pk_bf16_f32 v67, v70, v71
	v_permlane16_swap_b32_e32 v64, v66
	s_nop 0
	v_permlane16_swap_b32_e32 v65, v67
	global_store_dwordx4 v[76:77], v[64:67], off offset:256 sc1

.LBB0_611:
	v_ashrrev_i32_e32 v65, 7, v64
	v_and_b32_e32 v82, -2, v65
	s_and_b64 vcc, exec, s[50:51]
	v_ashrrev_i32_e32 v65, 31, v64
	v_pk_mul_f32 v[76:77], v[56:57], v[68:69]
	v_pk_mul_f32 v[74:75], v[56:57], v[66:67]
	s_cbranch_vccnz .LBB0_655
	v_pk_mul_f32 v[84:85], v[58:59], v[70:71]
	v_pk_fma_f32 v[78:79], v[60:61], v[66:67], v[76:77] neg_lo:[0,0,1] neg_hi:[0,0,1]
	v_pk_fma_f32 v[86:87], v[62:63], v[72:73], v[84:85] neg_lo:[0,0,1] neg_hi:[0,0,1]
	v_pk_mul_f32 v[84:85], v[58:59], v[72:73]
	v_pk_fma_f32 v[80:81], v[60:61], v[68:69], v[74:75]
	v_pk_fma_f32 v[88:89], v[62:63], v[70:71], v[84:85]
	v_lshlrev_b64 v[90:91], 9, v[64:65]
	v_cvt_pk_bf16_f32 v84, v78, v79
	v_cvt_pk_bf16_f32 v85, v86, v87
	v_cvt_pk_bf16_f32 v86, v80, v81
	v_cvt_pk_bf16_f32 v87, v88, v89
	v_lshlrev_b32_e32 v78, 9, v64
	v_permlane16_swap_b32_e32 v84, v86
	v_permlane16_swap_b32_e32 v85, v87
	v_lshl_add_u64 v[80:81], v[144:145], 0, v[90:91]
	s_and_b64 vcc, exec, s[46:47]
	v_and_b32_e32 v78, 0x19e00, v78
	global_store_dwordx4 v[80:81], v[84:87], off sc1
	s_cbranch_vccnz .LBB0_614
	v_readlane_b32 s4, v255, 6
	v_readlane_b32 s5, v255, 7
	v_mov_b32_e32 v79, v209
	v_add_u32_e32 v84, s4, v82
	v_ashrrev_i32_e32 v85, 31, v84
	v_readlane_b32 s4, v254, 1
	v_lshlrev_b64 v[84:85], 17, v[84:85]
	v_readlane_b32 s5, v254, 2
	s_lshl_b32 s36, s2, 2
	v_lshlrev_b32_e32 v86, 2, v140
	v_lshl_add_u64 v[84:85], s[4:5], 0, v[84:85]
	v_lshl_add_u64 v[84:85], v[84:85], 0, v[78:79]
	v_lshl_add_u64 v[84:85], v[84:85], 0, s[36:37]
	v_mov_b32_e32 v87, v209
	v_lshl_add_u64 v[84:85], v[84:85], 0, v[86:87]
	global_store_dwordx4 v[84:85], v[60:63], off sc1
	global_store_dwordx4 v[84:85], v[56:59], off offset:64 sc1
.LBB0_614:
	s_nop 0
	v_cvt_pk_bf16_f32 v84, v52, v53
	v_cvt_pk_bf16_f32 v85, v54, v55
	v_cvt_pk_bf16_f32 v86, v48, v49
	v_cvt_pk_bf16_f32 v87, v50, v51
	s_nop 0
	v_permlane16_swap_b32_e32 v84, v86
	v_permlane16_swap_b32_e32 v85, v87
	s_and_b64 vcc, exec, s[46:47]
	global_store_dwordx4 v[80:81], v[84:87], off offset:256 sc1
	s_cbranch_vccnz .LBB0_616
	v_readlane_b32 s4, v255, 6
	v_readlane_b32 s5, v255, 7
	v_mov_b32_e32 v79, v209
	v_add_u32_e32 v56, s4, v82
	v_ashrrev_i32_e32 v57, 31, v56
	v_readlane_b32 s4, v254, 3
	v_lshlrev_b64 v[56:57], 17, v[56:57]
	v_readlane_b32 s5, v254, 4
	s_lshl_b32 s36, s2, 2
	s_nop 0
	v_lshl_add_u64 v[56:57], s[4:5], 0, v[56:57]
	v_lshl_add_u64 v[56:57], v[56:57], 0, v[78:79]
	v_lshl_add_u64 v[56:57], v[56:57], 0, s[36:37]
	v_lshlrev_b32_e32 v78, 2, v140
	v_lshl_add_u64 v[56:57], v[56:57], 0, v[78:79]
	global_store_dwordx4 v[56:57], v[52:55], off sc1
	global_store_dwordx4 v[56:57], v[48:51], off offset:64 sc1

.LBB0_617:
	v_lshlrev_b64 v[56:57], 10, v[64:65]
	s_lshl_b32 s18, s17, 8
	v_pk_fma_f32 v[76:77], v[60:61], v[66:67], v[76:77] neg_lo:[0,0,1] neg_hi:[0,0,1]
	v_pk_fma_f32 v[60:61], v[60:61], v[68:69], v[74:75]
	v_pk_mul_f32 v[74:75], v[58:59], v[70:71]
	v_pk_mul_f32 v[58:59], v[58:59], v[72:73]
	v_lshl_add_u64 v[56:57], s[56:57], 0, v[56:57]
	s_ashr_i32 s19, s18, 31
	v_pk_fma_f32 v[74:75], v[62:63], v[72:73], v[74:75] neg_lo:[0,0,1] neg_hi:[0,0,1]
	v_pk_fma_f32 v[58:59], v[62:63], v[70:71], v[58:59]
	v_lshl_add_u64 v[56:57], s[18:19], 1, v[56:57]
	s_lshl_b32 s36, s2, 1
	v_pk_mul_f32 v[76:77], v[76:77], s[22:23] op_sel_hi:[1,0]
	v_pk_mul_f32 v[60:61], v[60:61], s[22:23] op_sel_hi:[1,0]
	v_pk_mul_f32 v[74:75], v[74:75], s[22:23] op_sel_hi:[1,0]
	v_pk_mul_f32 v[62:63], v[58:59], s[22:23] op_sel_hi:[1,0]
	v_lshl_add_u64 v[56:57], v[56:57], 0, s[36:37]
	v_lshl_add_u64 v[78:79], v[56:57], 0, v[208:209]
	v_cvt_pk_bf16_f32 v56, v76, v77
	v_cvt_pk_bf16_f32 v57, v74, v75
	v_cvt_pk_bf16_f32 v58, v60, v61
	v_cvt_pk_bf16_f32 v59, v62, v63
	s_nop 0
	v_permlane16_swap_b32_e32 v56, v58
	v_permlane16_swap_b32_e32 v57, v59
	v_lshl_add_u64 v[60:61], v[78:79], 0, v[142:143]
	global_store_dwordx4 v[60:61], v[56:59], off sc1
	s_nop 1
	v_pk_mul_f32 v[56:57], v[48:49], v[68:69]
	v_pk_mul_f32 v[48:49], v[48:49], v[66:67]
	v_pk_fma_f32 v[56:57], v[52:53], v[66:67], v[56:57] neg_lo:[0,0,1] neg_hi:[0,0,1]
	v_pk_fma_f32 v[48:49], v[52:53], v[68:69], v[48:49]
	v_pk_mul_f32 v[56:57], v[56:57], s[22:23] op_sel_hi:[1,0]
	v_pk_mul_f32 v[52:53], v[48:49], s[22:23] op_sel_hi:[1,0]
	v_pk_mul_f32 v[48:49], v[50:51], v[70:71]
	s_nop 0
	v_pk_fma_f32 v[48:49], v[54:55], v[72:73], v[48:49] neg_lo:[0,0,1] neg_hi:[0,0,1]
	s_nop 0
	v_pk_mul_f32 v[58:59], v[48:49], s[22:23] op_sel_hi:[1,0]
	v_pk_mul_f32 v[48:49], v[50:51], v[72:73]
	v_cvt_pk_bf16_f32 v50, v52, v53
	v_pk_fma_f32 v[48:49], v[54:55], v[70:71], v[48:49]
	s_nop 0
	v_pk_mul_f32 v[54:55], v[48:49], s[22:23] op_sel_hi:[1,0]
	v_cvt_pk_bf16_f32 v48, v56, v57
	v_cvt_pk_bf16_f32 v49, v58, v59
	v_cvt_pk_bf16_f32 v51, v54, v55
	v_permlane16_swap_b32_e32 v48, v50
	s_nop 0
	v_permlane16_swap_b32_e32 v49, v51
	global_store_dwordx4 v[60:61], v[48:51], off offset:256 sc1

.LBB0_621:
	s_and_b64 vcc, exec, s[50:51]
	v_ashrrev_i32_e32 v57, 31, v56
	v_pk_mul_f32 v[60:61], v[40:41], v[50:51]
	v_pk_mul_f32 v[58:59], v[40:41], v[48:49]
	s_cbranch_vccnz .LBB0_656
	v_pk_mul_f32 v[68:69], v[42:43], v[52:53]
	v_pk_fma_f32 v[62:63], v[44:45], v[48:49], v[60:61] neg_lo:[0,0,1] neg_hi:[0,0,1]
	v_pk_fma_f32 v[70:71], v[46:47], v[54:55], v[68:69] neg_lo:[0,0,1] neg_hi:[0,0,1]
	v_pk_mul_f32 v[68:69], v[42:43], v[54:55]
	v_pk_fma_f32 v[64:65], v[44:45], v[50:51], v[58:59]
	v_pk_fma_f32 v[72:73], v[46:47], v[52:53], v[68:69]
	v_lshlrev_b64 v[74:75], 9, v[56:57]
	v_cvt_pk_bf16_f32 v68, v62, v63
	v_cvt_pk_bf16_f32 v69, v70, v71
	v_cvt_pk_bf16_f32 v70, v64, v65
	v_cvt_pk_bf16_f32 v71, v72, v73
	v_lshlrev_b32_e32 v62, 9, v56
	v_permlane16_swap_b32_e32 v68, v70
	v_permlane16_swap_b32_e32 v69, v71
	v_lshl_add_u64 v[64:65], v[144:145], 0, v[74:75]
	s_and_b64 vcc, exec, s[46:47]
	v_and_b32_e32 v62, 0x1be00, v62
	global_store_dwordx4 v[64:65], v[68:71], off sc1
	s_cbranch_vccnz .LBB0_624
	v_readlane_b32 s4, v255, 6
	v_readlane_b32 s5, v255, 7
	v_mov_b32_e32 v63, v209
	v_add_u32_e32 v68, s4, v82
	v_ashrrev_i32_e32 v69, 31, v68
	v_readlane_b32 s4, v254, 1
	v_lshlrev_b64 v[68:69], 17, v[68:69]
	v_readlane_b32 s5, v254, 2
	s_lshl_b32 s36, s2, 2
	v_lshlrev_b32_e32 v70, 2, v140
	v_lshl_add_u64 v[68:69], s[4:5], 0, v[68:69]
	v_lshl_add_u64 v[68:69], v[68:69], 0, v[62:63]
	v_lshl_add_u64 v[68:69], v[68:69], 0, s[36:37]
	v_mov_b32_e32 v71, v209
	v_lshl_add_u64 v[68:69], v[68:69], 0, v[70:71]
	global_store_dwordx4 v[68:69], v[44:47], off sc1
	global_store_dwordx4 v[68:69], v[40:43], off offset:64 sc1
.LBB0_624:
	s_nop 0
	v_cvt_pk_bf16_f32 v68, v36, v37
	v_cvt_pk_bf16_f32 v69, v38, v39
	v_cvt_pk_bf16_f32 v70, v32, v33
	v_cvt_pk_bf16_f32 v71, v34, v35
	s_nop 0
	v_permlane16_swap_b32_e32 v68, v70
	v_permlane16_swap_b32_e32 v69, v71
	s_and_b64 vcc, exec, s[46:47]
	global_store_dwordx4 v[64:65], v[68:71], off offset:256 sc1
	s_cbranch_vccnz .LBB0_626
	v_readlane_b32 s4, v255, 6
	v_readlane_b32 s5, v255, 7
	v_mov_b32_e32 v63, v209
	v_add_u32_e32 v40, s4, v82
	v_ashrrev_i32_e32 v41, 31, v40
	v_readlane_b32 s4, v254, 3
	v_lshlrev_b64 v[40:41], 17, v[40:41]
	v_readlane_b32 s5, v254, 4
	s_lshl_b32 s36, s2, 2
	s_nop 0
	v_lshl_add_u64 v[40:41], s[4:5], 0, v[40:41]
	v_lshl_add_u64 v[40:41], v[40:41], 0, v[62:63]
	v_lshl_add_u64 v[40:41], v[40:41], 0, s[36:37]
	v_lshlrev_b32_e32 v62, 2, v140
	v_lshl_add_u64 v[40:41], v[40:41], 0, v[62:63]
	global_store_dwordx4 v[40:41], v[36:39], off sc1
	global_store_dwordx4 v[40:41], v[32:35], off offset:64 sc1

.LBB0_627:
	v_lshlrev_b64 v[40:41], 10, v[56:57]
	s_lshl_b32 s18, s17, 8
	v_pk_fma_f32 v[56:57], v[44:45], v[48:49], v[60:61] neg_lo:[0,0,1] neg_hi:[0,0,1]
	v_pk_fma_f32 v[44:45], v[44:45], v[50:51], v[58:59]
	v_pk_mul_f32 v[58:59], v[42:43], v[52:53]
	v_pk_mul_f32 v[42:43], v[42:43], v[54:55]
	v_lshl_add_u64 v[40:41], s[56:57], 0, v[40:41]
	s_ashr_i32 s19, s18, 31
	v_pk_fma_f32 v[58:59], v[46:47], v[54:55], v[58:59] neg_lo:[0,0,1] neg_hi:[0,0,1]
	v_pk_fma_f32 v[42:43], v[46:47], v[52:53], v[42:43]
	v_lshl_add_u64 v[40:41], s[18:19], 1, v[40:41]
	s_lshl_b32 s36, s2, 1
	v_pk_mul_f32 v[56:57], v[56:57], s[22:23] op_sel_hi:[1,0]
	v_pk_mul_f32 v[44:45], v[44:45], s[22:23] op_sel_hi:[1,0]
	v_pk_mul_f32 v[58:59], v[58:59], s[22:23] op_sel_hi:[1,0]
	v_pk_mul_f32 v[46:47], v[42:43], s[22:23] op_sel_hi:[1,0]
	v_lshl_add_u64 v[40:41], v[40:41], 0, s[36:37]
	v_lshl_add_u64 v[60:61], v[40:41], 0, v[208:209]
	v_cvt_pk_bf16_f32 v40, v56, v57
	v_cvt_pk_bf16_f32 v41, v58, v59
	v_cvt_pk_bf16_f32 v42, v44, v45
	v_cvt_pk_bf16_f32 v43, v46, v47
	s_nop 0
	v_permlane16_swap_b32_e32 v40, v42
	v_permlane16_swap_b32_e32 v41, v43
	v_lshl_add_u64 v[44:45], v[60:61], 0, v[142:143]
	global_store_dwordx4 v[44:45], v[40:43], off sc1
	s_nop 1
	v_pk_mul_f32 v[40:41], v[32:33], v[50:51]
	v_pk_mul_f32 v[32:33], v[32:33], v[48:49]
	v_pk_fma_f32 v[40:41], v[36:37], v[48:49], v[40:41] neg_lo:[0,0,1] neg_hi:[0,0,1]
	v_pk_fma_f32 v[32:33], v[36:37], v[50:51], v[32:33]
	v_pk_mul_f32 v[40:41], v[40:41], s[22:23] op_sel_hi:[1,0]
	v_pk_mul_f32 v[36:37], v[32:33], s[22:23] op_sel_hi:[1,0]
	v_pk_mul_f32 v[32:33], v[34:35], v[52:53]
	s_nop 0
	v_pk_fma_f32 v[32:33], v[38:39], v[54:55], v[32:33] neg_lo:[0,0,1] neg_hi:[0,0,1]
	s_nop 0
	v_pk_mul_f32 v[42:43], v[32:33], s[22:23] op_sel_hi:[1,0]
	v_pk_mul_f32 v[32:33], v[34:35], v[54:55]
	v_cvt_pk_bf16_f32 v34, v36, v37
	v_pk_fma_f32 v[32:33], v[38:39], v[52:53], v[32:33]
	s_nop 0
	v_pk_mul_f32 v[38:39], v[32:33], s[22:23] op_sel_hi:[1,0]
	v_cvt_pk_bf16_f32 v32, v40, v41
	v_cvt_pk_bf16_f32 v33, v42, v43
	v_cvt_pk_bf16_f32 v35, v38, v39
	v_permlane16_swap_b32_e32 v32, v34
	s_nop 0
	v_permlane16_swap_b32_e32 v33, v35
	global_store_dwordx4 v[44:45], v[32:35], off offset:256 sc1

.LBB0_631:
	s_and_b64 vcc, exec, s[50:51]
	v_ashrrev_i32_e32 v41, 31, v40
	v_pk_mul_f32 v[44:45], v[24:25], v[34:35]
	v_pk_mul_f32 v[42:43], v[24:25], v[32:33]
	s_cbranch_vccnz .LBB0_657
	v_pk_mul_f32 v[50:51], v[26:27], v[36:37]
	v_pk_fma_f32 v[46:47], v[28:29], v[32:33], v[44:45] neg_lo:[0,0,1] neg_hi:[0,0,1]
	v_pk_fma_f32 v[52:53], v[30:31], v[38:39], v[50:51] neg_lo:[0,0,1] neg_hi:[0,0,1]
	v_pk_mul_f32 v[50:51], v[26:27], v[38:39]
	v_pk_fma_f32 v[48:49], v[28:29], v[34:35], v[42:43]
	v_pk_fma_f32 v[54:55], v[30:31], v[36:37], v[50:51]
	v_lshlrev_b64 v[56:57], 9, v[40:41]
	v_cvt_pk_bf16_f32 v50, v46, v47
	v_cvt_pk_bf16_f32 v51, v52, v53
	v_cvt_pk_bf16_f32 v52, v48, v49
	v_cvt_pk_bf16_f32 v53, v54, v55
	v_lshlrev_b32_e32 v46, 9, v40
	v_permlane16_swap_b32_e32 v50, v52
	v_permlane16_swap_b32_e32 v51, v53
	v_lshl_add_u64 v[48:49], v[144:145], 0, v[56:57]
	s_and_b64 vcc, exec, s[46:47]
	v_and_b32_e32 v46, 0x1de00, v46
	global_store_dwordx4 v[48:49], v[50:53], off sc1
	s_cbranch_vccnz .LBB0_634
	v_readlane_b32 s4, v255, 6
	v_readlane_b32 s5, v255, 7
	v_mov_b32_e32 v47, v209
	v_add_u32_e32 v50, s4, v82
	v_ashrrev_i32_e32 v51, 31, v50
	v_readlane_b32 s4, v254, 1
	v_lshlrev_b64 v[50:51], 17, v[50:51]
	v_readlane_b32 s5, v254, 2
	s_lshl_b32 s36, s2, 2
	v_lshlrev_b32_e32 v52, 2, v140
	v_lshl_add_u64 v[50:51], s[4:5], 0, v[50:51]
	v_lshl_add_u64 v[50:51], v[50:51], 0, v[46:47]
	v_lshl_add_u64 v[50:51], v[50:51], 0, s[36:37]
	v_mov_b32_e32 v53, v209
	v_lshl_add_u64 v[50:51], v[50:51], 0, v[52:53]
	global_store_dwordx4 v[50:51], v[28:31], off sc1
	global_store_dwordx4 v[50:51], v[24:27], off offset:64 sc1
.LBB0_634:
	s_nop 0
	v_cvt_pk_bf16_f32 v50, v20, v21
	v_cvt_pk_bf16_f32 v51, v22, v23
	v_cvt_pk_bf16_f32 v52, v16, v17
	v_cvt_pk_bf16_f32 v53, v18, v19
	s_nop 0
	v_permlane16_swap_b32_e32 v50, v52
	v_permlane16_swap_b32_e32 v51, v53
	s_and_b64 vcc, exec, s[46:47]
	global_store_dwordx4 v[48:49], v[50:53], off offset:256 sc1
	s_cbranch_vccnz .LBB0_636
	v_readlane_b32 s4, v255, 6
	v_readlane_b32 s5, v255, 7
	v_mov_b32_e32 v47, v209
	v_add_u32_e32 v24, s4, v82
	v_ashrrev_i32_e32 v25, 31, v24
	v_readlane_b32 s4, v254, 3
	v_lshlrev_b64 v[24:25], 17, v[24:25]
	v_readlane_b32 s5, v254, 4
	s_lshl_b32 s36, s2, 2
	s_nop 0
	v_lshl_add_u64 v[24:25], s[4:5], 0, v[24:25]
	v_lshl_add_u64 v[24:25], v[24:25], 0, v[46:47]
	v_lshl_add_u64 v[24:25], v[24:25], 0, s[36:37]
	v_lshlrev_b32_e32 v46, 2, v140
	v_lshl_add_u64 v[24:25], v[24:25], 0, v[46:47]
	global_store_dwordx4 v[24:25], v[20:23], off sc1
	global_store_dwordx4 v[24:25], v[16:19], off offset:64 sc1

.LBB0_637:
	v_lshlrev_b64 v[24:25], 10, v[40:41]
	s_lshl_b32 s18, s17, 8
	v_pk_fma_f32 v[40:41], v[28:29], v[32:33], v[44:45] neg_lo:[0,0,1] neg_hi:[0,0,1]
	v_pk_fma_f32 v[28:29], v[28:29], v[34:35], v[42:43]
	v_pk_mul_f32 v[42:43], v[26:27], v[36:37]
	v_pk_mul_f32 v[26:27], v[26:27], v[38:39]
	v_lshl_add_u64 v[24:25], s[56:57], 0, v[24:25]
	s_ashr_i32 s19, s18, 31
	v_pk_fma_f32 v[42:43], v[30:31], v[38:39], v[42:43] neg_lo:[0,0,1] neg_hi:[0,0,1]
	v_pk_fma_f32 v[26:27], v[30:31], v[36:37], v[26:27]
	v_lshl_add_u64 v[24:25], s[18:19], 1, v[24:25]
	s_lshl_b32 s36, s2, 1
	v_pk_mul_f32 v[40:41], v[40:41], s[22:23] op_sel_hi:[1,0]
	v_pk_mul_f32 v[28:29], v[28:29], s[22:23] op_sel_hi:[1,0]
	v_pk_mul_f32 v[42:43], v[42:43], s[22:23] op_sel_hi:[1,0]
	v_pk_mul_f32 v[30:31], v[26:27], s[22:23] op_sel_hi:[1,0]
	v_lshl_add_u64 v[24:25], v[24:25], 0, s[36:37]
	v_lshl_add_u64 v[44:45], v[24:25], 0, v[208:209]
	v_cvt_pk_bf16_f32 v24, v40, v41
	v_cvt_pk_bf16_f32 v25, v42, v43
	v_cvt_pk_bf16_f32 v26, v28, v29
	v_cvt_pk_bf16_f32 v27, v30, v31
	s_nop 0
	v_permlane16_swap_b32_e32 v24, v26
	v_permlane16_swap_b32_e32 v25, v27
	v_lshl_add_u64 v[28:29], v[44:45], 0, v[142:143]
	global_store_dwordx4 v[28:29], v[24:27], off sc1
	s_nop 1
	v_pk_mul_f32 v[24:25], v[16:17], v[34:35]
	v_pk_mul_f32 v[16:17], v[16:17], v[32:33]
	v_pk_fma_f32 v[24:25], v[20:21], v[32:33], v[24:25] neg_lo:[0,0,1] neg_hi:[0,0,1]
	v_pk_fma_f32 v[16:17], v[20:21], v[34:35], v[16:17]
	v_pk_mul_f32 v[24:25], v[24:25], s[22:23] op_sel_hi:[1,0]
	v_pk_mul_f32 v[20:21], v[16:17], s[22:23] op_sel_hi:[1,0]
	v_pk_mul_f32 v[16:17], v[18:19], v[36:37]
	s_nop 0
	v_pk_fma_f32 v[16:17], v[22:23], v[38:39], v[16:17] neg_lo:[0,0,1] neg_hi:[0,0,1]
	s_nop 0
	v_pk_mul_f32 v[26:27], v[16:17], s[22:23] op_sel_hi:[1,0]
	v_pk_mul_f32 v[16:17], v[18:19], v[38:39]
	v_cvt_pk_bf16_f32 v18, v20, v21
	v_pk_fma_f32 v[16:17], v[22:23], v[36:37], v[16:17]
	s_nop 0
	v_pk_mul_f32 v[22:23], v[16:17], s[22:23] op_sel_hi:[1,0]
	v_cvt_pk_bf16_f32 v16, v24, v25
	v_cvt_pk_bf16_f32 v17, v26, v27
	v_cvt_pk_bf16_f32 v19, v22, v23
	v_permlane16_swap_b32_e32 v16, v18
	s_nop 0
	v_permlane16_swap_b32_e32 v17, v19
	global_store_dwordx4 v[28:29], v[16:19], off offset:256 sc1

.LBB0_641:
	s_and_b64 vcc, exec, s[50:51]
	v_ashrrev_i32_e32 v25, 31, v24
	v_pk_mul_f32 v[28:29], v[8:9], v[18:19]
	v_pk_mul_f32 v[26:27], v[8:9], v[16:17]
	s_cbranch_vccnz .LBB0_658
	v_pk_mul_f32 v[34:35], v[10:11], v[20:21]
	v_pk_mul_f32 v[36:37], v[10:11], v[22:23]
	v_pk_fma_f32 v[30:31], v[12:13], v[16:17], v[28:29] neg_lo:[0,0,1] neg_hi:[0,0,1]
	v_pk_fma_f32 v[32:33], v[12:13], v[18:19], v[26:27]
	v_pk_fma_f32 v[34:35], v[14:15], v[22:23], v[34:35] neg_lo:[0,0,1] neg_hi:[0,0,1]
	v_pk_fma_f32 v[36:37], v[14:15], v[20:21], v[36:37]
	v_lshlrev_b64 v[38:39], 9, v[24:25]
	v_cvt_pk_bf16_f32 v30, v30, v31
	v_cvt_pk_bf16_f32 v31, v34, v35
	v_cvt_pk_bf16_f32 v32, v32, v33
	v_cvt_pk_bf16_f32 v33, v36, v37
	s_nop 0
	v_permlane16_swap_b32_e32 v30, v32
	v_permlane16_swap_b32_e32 v31, v33
	v_lshl_add_u64 v[36:37], v[144:145], 0, v[38:39]
	v_readlane_b32 s4, v255, 6
	global_store_dwordx4 v[36:37], v[30:33], off sc1
	s_and_b64 vcc, exec, s[46:47]
	v_add_u32_e32 v34, s4, v82
	v_lshlrev_b32_e32 v30, 9, v24
	v_ashrrev_i32_e32 v35, 31, v34
	v_and_b32_e32 v32, 0x1fe00, v30
	v_lshlrev_b32_e32 v30, 2, v140
	v_readlane_b32 s5, v255, 7
	s_cbranch_vccnz .LBB0_644
	v_readlane_b32 s4, v254, 1
	v_lshlrev_b64 v[38:39], 17, v[34:35]
	v_readlane_b32 s5, v254, 2
	v_mov_b32_e32 v33, v209
	s_lshl_b32 s36, s2, 2
	v_lshl_add_u64 v[38:39], s[4:5], 0, v[38:39]
	v_lshl_add_u64 v[38:39], v[38:39], 0, v[32:33]
	v_lshl_add_u64 v[38:39], v[38:39], 0, s[36:37]
	v_mov_b32_e32 v31, v209
	v_lshl_add_u64 v[38:39], v[38:39], 0, v[30:31]
	global_store_dwordx4 v[38:39], v[12:15], off sc1
	global_store_dwordx4 v[38:39], v[8:11], off offset:64 sc1
.LBB0_644:
	v_cvt_pk_bf16_f32 v38, v4, v5
	v_cvt_pk_bf16_f32 v39, v6, v7
	v_cvt_pk_bf16_f32 v40, v0, v1
	v_cvt_pk_bf16_f32 v41, v2, v3
	s_nop 0
	v_permlane16_swap_b32_e32 v38, v40
	v_permlane16_swap_b32_e32 v39, v41
	s_and_b64 vcc, exec, s[46:47]
	global_store_dwordx4 v[36:37], v[38:41], off offset:256 sc1
	s_cbranch_vccnz .LBB0_646
	v_readlane_b32 s4, v254, 3
	v_lshlrev_b64 v[8:9], 17, v[34:35]
	v_readlane_b32 s5, v254, 4
	v_mov_b32_e32 v33, v209
	s_lshl_b32 s36, s2, 2
	v_lshl_add_u64 v[8:9], s[4:5], 0, v[8:9]
	v_lshl_add_u64 v[8:9], v[8:9], 0, v[32:33]
	v_lshl_add_u64 v[8:9], v[8:9], 0, s[36:37]
	v_mov_b32_e32 v31, v209
	v_lshl_add_u64 v[8:9], v[8:9], 0, v[30:31]
	global_store_dwordx4 v[8:9], v[4:7], off sc1
	global_store_dwordx4 v[8:9], v[0:3], off offset:64 sc1

.LBB0_647:
	v_lshlrev_b64 v[8:9], 10, v[24:25]
	s_lshl_b32 s16, s17, 8
	v_pk_fma_f32 v[24:25], v[12:13], v[16:17], v[28:29] neg_lo:[0,0,1] neg_hi:[0,0,1]
	v_pk_fma_f32 v[12:13], v[12:13], v[18:19], v[26:27]
	v_pk_mul_f32 v[26:27], v[10:11], v[20:21]
	v_pk_mul_f32 v[10:11], v[10:11], v[22:23]
	v_lshl_add_u64 v[8:9], s[56:57], 0, v[8:9]
	s_ashr_i32 s17, s16, 31
	v_pk_fma_f32 v[26:27], v[14:15], v[22:23], v[26:27] neg_lo:[0,0,1] neg_hi:[0,0,1]
	v_pk_fma_f32 v[10:11], v[14:15], v[20:21], v[10:11]
	v_lshl_add_u64 v[8:9], s[16:17], 1, v[8:9]
	s_lshl_b32 s36, s2, 1
	v_pk_mul_f32 v[24:25], v[24:25], s[22:23] op_sel_hi:[1,0]
	v_pk_mul_f32 v[12:13], v[12:13], s[22:23] op_sel_hi:[1,0]
	v_pk_mul_f32 v[26:27], v[26:27], s[22:23] op_sel_hi:[1,0]
	v_pk_mul_f32 v[14:15], v[10:11], s[22:23] op_sel_hi:[1,0]
	v_lshl_add_u64 v[8:9], v[8:9], 0, s[36:37]
	v_lshl_add_u64 v[28:29], v[8:9], 0, v[208:209]
	v_cvt_pk_bf16_f32 v8, v24, v25
	v_cvt_pk_bf16_f32 v9, v26, v27
	v_cvt_pk_bf16_f32 v10, v12, v13
	v_cvt_pk_bf16_f32 v11, v14, v15
	s_nop 0
	v_permlane16_swap_b32_e32 v8, v10
	v_permlane16_swap_b32_e32 v9, v11
	v_lshl_add_u64 v[12:13], v[28:29], 0, v[142:143]
	global_store_dwordx4 v[12:13], v[8:11], off sc1
	s_nop 1
	v_pk_mul_f32 v[8:9], v[0:1], v[18:19]
	v_pk_mul_f32 v[0:1], v[0:1], v[16:17]
	v_pk_fma_f32 v[8:9], v[4:5], v[16:17], v[8:9] neg_lo:[0,0,1] neg_hi:[0,0,1]
	v_pk_fma_f32 v[0:1], v[4:5], v[18:19], v[0:1]
	v_pk_mul_f32 v[8:9], v[8:9], s[22:23] op_sel_hi:[1,0]
	v_pk_mul_f32 v[4:5], v[0:1], s[22:23] op_sel_hi:[1,0]
	v_pk_mul_f32 v[0:1], v[2:3], v[20:21]
	s_nop 0
	v_pk_fma_f32 v[0:1], v[6:7], v[22:23], v[0:1] neg_lo:[0,0,1] neg_hi:[0,0,1]
	s_nop 0
	v_pk_mul_f32 v[10:11], v[0:1], s[22:23] op_sel_hi:[1,0]
	v_pk_mul_f32 v[0:1], v[2:3], v[22:23]
	v_cvt_pk_bf16_f32 v2, v4, v5
	v_pk_fma_f32 v[0:1], v[6:7], v[20:21], v[0:1]
	s_nop 0
	v_pk_mul_f32 v[6:7], v[0:1], s[22:23] op_sel_hi:[1,0]
	v_cvt_pk_bf16_f32 v0, v8, v9
	v_cvt_pk_bf16_f32 v1, v10, v11
	v_cvt_pk_bf16_f32 v3, v6, v7
	v_permlane16_swap_b32_e32 v0, v2
	s_nop 0
	v_permlane16_swap_b32_e32 v1, v3
	global_store_dwordx4 v[12:13], v[0:3], off offset:256 sc1
